# P7 epilogue variant: halo blend via v_cndmask then one row_ror DPP fmac per tap (half the DPP ops of the previous version)
# speedup vs baseline: 1.0107x; 1.0015x over previous
; #define PG8_LAS __attribute__((address_space(3)))
; __device__ __forceinline__ float row_rstd(const float* slots, int row) {
;     const f32x4* s = (const f32x4*)(slots + (size_t)row * 16);
;     const f32x4 a = s[0], b = s[1], c = s[2], d = s[3];
;     const f32x4 t = (a + b) + (c + d);
;     const float ss = (t[0] + t[1]) + (t[2] + t[3]);
;     return __builtin_amdgcn_rsqf(ss * (1.0f / 1024.0f) + 1e-6f);
; }
; __device__ __forceinline__ void load_rs(const float* slots, int rowbase, int fr, int fq, float scale, float (&rs)[2][4]) {
;     float loc[2];
; #pragma unroll
;     for (int ai = 0; ai < 2; ++ai) loc[ai] = scale * row_rstd(slots, rowbase + ai * HALF + fq * 16 + fr);
; #pragma unroll
;     for (int ai = 0; ai < 2; ++ai)
; #pragma unroll
;         for (int m = 0; m < 4; ++m) rs[ai][m] = __shfl(loc[ai], m * 16 + fr);
;     __device__ __forceinline__ void operator()(const f32x4 (&acc)[2][2][4][2], const Unit& u, int wr, int wc, int fr, int fq) const {
;         constexpr int FF = 2816, FF2 = 5632;
;         const int lcol = wc * 32 + 8 * fq, gcol = u.pn * HALF + lcol;
;         float rs[2][4];
;         load_rs(slots, u.pm * BM + wr * 64, fr, fq, 1.0f, rs);
;         if (fr >= 14) {
; #pragma unroll
;             for (int ai = 0; ai < 2; ++ai)
; #pragma unroll
;                 for (int bj = 0; bj < 2; ++bj)
; #pragma unroll
;                     for (int n = 0; n < 2; ++n) { const f32x4 x = acc[ai][bj][3][n] * rs[ai][3];
;                         *(PG8_LAS f32x4*)(halo + ((ai * 2 + wr) * 2 + (fr - 14)) * 256 + bj * HALF + lcol + 4 * n) = x;
;                         if (ai == 1 && wr == 1) *(f32x4*)(rawh + (size_t)(u.pm * 2 + (fr - 14)) * FF2 + bj * FF + gcol + 4 * n) = x; }
;         }
;         f32x4 w0[2], w1[2], w2[2], bb[2];
; #pragma unroll
;         for (int bj = 0; bj < 2; ++bj) { const int col = bj * FF + gcol;
;             w0[bj] = *(const f32x4*)(cw + col); w1[bj] = *(const f32x4*)(cw + FF2 + col); w2[bj] = *(const f32x4*)(cw + 2 * FF2 + col); bb[bj] = *(const f32x4*)(cb + col); }
;         asm volatile("s_waitcnt lgkmcnt(0)" ::: "memory"); __builtin_amdgcn_s_barrier(); asm volatile("" ::: "memory");
;         unsigned pk_lo[2][4][2];
; #pragma unroll
;         for (int n = 0; n < 2; ++n) {
;             if (n == 1) {
; #pragma unroll
;                 for (int bj = 0; bj < 2; ++bj) { const int col = bj * FF + gcol + 4;
.LBB0_900:
	v_readlane_b32 s18, v255, 37
	v_readlane_b32 s19, v255, 38
	s_lshl_b32 s5, s71, 8
	s_add_i32 s5, s5, s8
	s_lshl_b32 s11, s71, 1
	s_movk_i32 s29, 0x1600
	s_mov_b32 s100, 0xbfb8aa3b
	v_cmp_eq_u32_e64 s[98:99], 15, v206
	v_or_b32_e32 v227, s5, v209
	v_lshl_or_b32 v231, s69, 7, v208
	v_lshlrev_b32_e32 v227, 6, v227
	v_lshlrev_b32_e32 v231, 2, v231
	v_add_u32_e32 v229, 0x2000, v227
	v_add_u32_e32 v233, 0x2c00, v231
	global_load_dwordx4 v[160:163], v227, s[26:27]
	global_load_dwordx4 v[164:167], v227, s[26:27] offset:16
	global_load_dwordx4 v[178:181], v227, s[26:27] offset:32
	global_load_dwordx4 v[182:185], v227, s[26:27] offset:48
	global_load_dwordx4 v[186:189], v229, s[26:27]
	global_load_dwordx4 v[194:197], v229, s[26:27] offset:16
	global_load_dwordx4 v[198:201], v229, s[26:27] offset:32
	global_load_dwordx4 v[202:205], v229, s[26:27] offset:48
	global_load_dwordx4 v[128:131], v231, s[14:15]
	global_load_dwordx4 v[132:135], v231, s[16:17]
	global_load_dwordx4 v[136:139], v231, s[92:93]
	global_load_dwordx4 v[140:143], v231, s[60:61]
	global_load_dwordx4 v[144:147], v233, s[14:15]
	global_load_dwordx4 v[148:151], v233, s[16:17]
	global_load_dwordx4 v[152:155], v233, s[92:93]
	global_load_dwordx4 v[156:159], v233, s[60:61]
	v_or_b32_e32 v237, s5, v206
	v_lshrrev_b32_e32 v243, 1, v231
	v_add_u32_e32 v239, s11, v206
	v_mad_u32_u24 v237, v237, s29, v243
	v_mad_u32_u24 v239, v239, s70, v231
	v_lshlrev_b32_e32 v235, 2, v206
	v_add_u32_e32 v241, 0x2c00, v239
	s_waitcnt vmcnt(8)
	v_pk_add_f32 v[162:163], v[162:163], v[166:167]
	v_pk_add_f32 v[188:189], v[188:189], v[196:197]
	v_pk_add_f32 v[160:161], v[160:161], v[164:165]
	v_pk_add_f32 v[186:187], v[186:187], v[194:195]
	v_pk_add_f32 v[164:165], v[180:181], v[184:185]
	v_pk_add_f32 v[194:195], v[200:201], v[204:205]
	v_pk_add_f32 v[166:167], v[178:179], v[182:183]
	v_pk_add_f32 v[196:197], v[198:199], v[202:203]
	v_pk_add_f32 v[162:163], v[162:163], v[164:165]
	v_pk_add_f32 v[188:189], v[188:189], v[194:195]
	v_pk_add_f32 v[160:161], v[160:161], v[166:167]
	v_pk_add_f32 v[186:187], v[186:187], v[196:197]
	v_add_f32_e32 v160, v160, v161
	v_add_f32_e32 v186, v186, v187
	v_add_f32_e32 v161, v162, v163
	v_add_f32_e32 v187, v188, v189
	v_add_f32_e32 v160, v160, v161
	v_add_f32_e32 v186, v186, v187
	v_fmamk_f32 v160, v160, 0x3a800000, v244
	v_fmamk_f32 v186, v186, 0x3a800000, v244
	v_rsq_f32_e32 v160, v160
	v_rsq_f32_e32 v186, v186
	ds_bpermute_b32 v226, v235, v160
	ds_bpermute_b32 v228, v235, v160 offset:64
	ds_bpermute_b32 v230, v235, v160 offset:128
	ds_bpermute_b32 v232, v235, v160 offset:192
	ds_bpermute_b32 v234, v235, v186
	ds_bpermute_b32 v236, v235, v186 offset:64
	ds_bpermute_b32 v238, v235, v186 offset:128
	ds_bpermute_b32 v240, v235, v186 offset:192
	s_waitcnt lgkmcnt(0)
	v_pk_mul_f32 v[100:101], v[100:101], v[232:233] op_sel_hi:[1,0]
	v_pk_mul_f32 v[102:103], v[102:103], v[232:233] op_sel_hi:[1,0]
	v_pk_mul_f32 v[36:37], v[36:37], v[232:233] op_sel_hi:[1,0]
	v_pk_mul_f32 v[38:39], v[38:39], v[232:233] op_sel_hi:[1,0]
	v_pk_mul_f32 v[96:97], v[96:97], v[232:233] op_sel_hi:[1,0]
	v_pk_mul_f32 v[98:99], v[98:99], v[232:233] op_sel_hi:[1,0]
	v_pk_mul_f32 v[32:33], v[32:33], v[232:233] op_sel_hi:[1,0]
	v_pk_mul_f32 v[34:35], v[34:35], v[232:233] op_sel_hi:[1,0]
	v_pk_mul_f32 v[68:69], v[68:69], v[240:241] op_sel_hi:[1,0]
	v_pk_mul_f32 v[70:71], v[70:71], v[240:241] op_sel_hi:[1,0]
	v_pk_mul_f32 v[4:5], v[4:5], v[240:241] op_sel_hi:[1,0]
	v_pk_mul_f32 v[6:7], v[6:7], v[240:241] op_sel_hi:[1,0]
	v_pk_mul_f32 v[64:65], v[64:65], v[240:241] op_sel_hi:[1,0]
	v_pk_mul_f32 v[66:67], v[66:67], v[240:241] op_sel_hi:[1,0]
	v_pk_mul_f32 v[0:1], v[0:1], v[240:241] op_sel_hi:[1,0]
	v_pk_mul_f32 v[2:3], v[2:3], v[240:241] op_sel_hi:[1,0]
	s_mov_b64 s[0:1], exec
	s_andn2_b64 exec, exec, s[40:41]
	ds_write_b128 v211, v[100:103]
	ds_write_b128 v211, v[36:39] offset:16
	ds_write_b128 v211, v[96:99] offset:512
	ds_write_b128 v211, v[32:35] offset:528
	ds_write_b128 v211, v[68:71] offset:4096
	ds_write_b128 v211, v[4:7] offset:4112
	ds_write_b128 v211, v[64:67] offset:4608
	ds_write_b128 v211, v[0:3] offset:4624
	s_mov_b64 exec, s[0:1]
	s_waitcnt lgkmcnt(0)
	s_barrier
	s_and_b64 vcc, exec, s[94:95]
	s_cbranch_vccnz .Lp7_hz0
	ds_read_b128 v[160:163], v213
	ds_read_b128 v[164:167], v213 offset:512
	s_branch .Lp7_hr0

; #define PG8_LAS __attribute__((address_space(3)))
; __device__ __forceinline__ unsigned cvt_pk_bf16(float lo, float hi) { unsigned r; asm volatile("v_cvt_pk_bf16_f32 %0, %1, %2" : "=v"(r) : "v"(lo), "v"(hi)); return r; }
; __device__ __forceinline__ float dpp_ror1(float x) { return __int_as_float(__builtin_amdgcn_update_dpp(0, __float_as_int(x), 0x121, 0xf, 0xf, false)); }
; __device__ __forceinline__ float dpp_ror2(float x) { return __int_as_float(__builtin_amdgcn_update_dpp(0, __float_as_int(x), 0x122, 0xf, 0xf, false)); }
;     __device__ __forceinline__ void operator()(const f32x4 (&acc)[2][2][4][2], const Unit& u, int wr, int wc, int fr, int fq) const {
;     ...
;                 f32x4 pg[2]; const int pb = ai * 2 + wr - 1;
; #pragma unroll
;                 for (int bj = 0; bj < 2; ++bj) { pg[bj] = (f32x4){0.f, 0.f, 0.f, 0.f};
;                     if (pb >= 0 && fr >= 14) pg[bj] = *(const PG8_LAS f32x4*)(halo + (pb * 2 + (fr - 14)) * 256 + bj * HALF + lcol + 4 * n); }
; #pragma unroll
;                 for (int m = 0; m < 4; ++m) {
;                     f32x4 cur[2], h[2];
; #pragma unroll
;                     for (int bj = 0; bj < 2; ++bj) { cur[bj] = acc[ai][bj][m][n] * rs[ai][m]; f32x4 x1, x2;
; #pragma unroll
;                         for (int e = 0; e < 4; ++e) { const float c1 = dpp_ror1(cur[bj][e]), p1 = dpp_ror1(pg[bj][e]), c2 = dpp_ror2(cur[bj][e]), p2 = dpp_ror2(pg[bj][e]);
;                             x1[e] = fr >= 1 ? c1 : p1; x2[e] = fr >= 2 ? c2 : p2; }
;                         h[bj] = bb[bj] + w0[bj] * x2 + w1[bj] * x1 + w2[bj] * cur[bj]; }
;                     if (ai == 0 && wr == 0 && m == 0 && fr < 2) {
;                         *(f32x4*)(hc0 + (size_t)(u.pm * 2 + fr) * FF2 + gcol + 4 * n) = h[0]; *(f32x4*)(hc0 + (size_t)(u.pm * 2 + fr) * FF2 + FF + gcol + 4 * n) = h[1]; }
;                     f32x4 a;
; #pragma unroll
;                     for (int e = 0; e < 4; ++e) { const float g = h[0][e]; a[e] = g * __builtin_amdgcn_rcpf(1.0f + __builtin_amdgcn_exp2f(-1.4426950408889634f * g)) * h[1][e]; }
;                     const unsigned p0 = cvt_pk_bf16(a[0], a[1]), p1 = cvt_pk_bf16(a[2], a[3]);
;                     if (n == 0) { pk_lo[ai][m][0] = p0; pk_lo[ai][m][1] = p1; }
.Lp7_hr0:
	ds_read_b128 v[178:181], v214
	ds_read_b128 v[182:185], v214 offset:512
	s_waitcnt vmcnt(0) lgkmcnt(0)
	v_pk_mul_f32 v[124:125], v[124:125], v[226:227] op_sel_hi:[1,0]
	v_pk_mul_f32 v[126:127], v[126:127], v[226:227] op_sel_hi:[1,0]
	v_pk_mul_f32 v[120:121], v[120:121], v[226:227] op_sel_hi:[1,0]
	v_pk_mul_f32 v[122:123], v[122:123], v[226:227] op_sel_hi:[1,0]
	v_pk_fma_f32 v[220:221], v[136:137], v[124:125], v[140:141]
	v_pk_fma_f32 v[222:223], v[138:139], v[126:127], v[142:143]
	v_pk_fma_f32 v[248:249], v[152:153], v[120:121], v[156:157]
	v_pk_fma_f32 v[250:251], v[154:155], v[122:123], v[158:159]
	v_cndmask_b32_e64 v188, v124, v160, s[98:99]
	v_cndmask_b32_e64 v189, v125, v161, s[98:99]
	v_cndmask_b32_e64 v196, v126, v162, s[98:99]
	v_cndmask_b32_e64 v197, v127, v163, s[98:99]
	v_cndmask_b32_e64 v200, v120, v164, s[98:99]
	v_cndmask_b32_e64 v201, v121, v165, s[98:99]
	v_cndmask_b32_e64 v204, v122, v166, s[98:99]
	v_cndmask_b32_e64 v205, v123, v167, s[98:99]
	v_fmac_f32_dpp v220, v188, v132 row_ror:1 row_mask:0xf bank_mask:0xf
	v_fmac_f32_dpp v221, v189, v133 row_ror:1 row_mask:0xf bank_mask:0xf
	v_fmac_f32_dpp v222, v196, v134 row_ror:1 row_mask:0xf bank_mask:0xf
	v_fmac_f32_dpp v223, v197, v135 row_ror:1 row_mask:0xf bank_mask:0xf
	v_fmac_f32_dpp v248, v200, v148 row_ror:1 row_mask:0xf bank_mask:0xf
	v_fmac_f32_dpp v249, v201, v149 row_ror:1 row_mask:0xf bank_mask:0xf
	v_fmac_f32_dpp v250, v204, v150 row_ror:1 row_mask:0xf bank_mask:0xf
	v_fmac_f32_dpp v251, v205, v151 row_ror:1 row_mask:0xf bank_mask:0xf
	v_cndmask_b32_e64 v188, v160, v124, s[40:41]
	v_cndmask_b32_e64 v189, v161, v125, s[40:41]
	v_cndmask_b32_e64 v196, v162, v126, s[40:41]
	v_cndmask_b32_e64 v197, v163, v127, s[40:41]
	v_cndmask_b32_e64 v200, v164, v120, s[40:41]
	v_cndmask_b32_e64 v201, v165, v121, s[40:41]
	v_cndmask_b32_e64 v204, v166, v122, s[40:41]
	v_cndmask_b32_e64 v205, v167, v123, s[40:41]
	v_fmac_f32_dpp v220, v188, v128 row_ror:2 row_mask:0xf bank_mask:0xf
	v_fmac_f32_dpp v221, v189, v129 row_ror:2 row_mask:0xf bank_mask:0xf
	v_fmac_f32_dpp v222, v196, v130 row_ror:2 row_mask:0xf bank_mask:0xf
	v_fmac_f32_dpp v223, v197, v131 row_ror:2 row_mask:0xf bank_mask:0xf
	v_fmac_f32_dpp v248, v200, v144 row_ror:2 row_mask:0xf bank_mask:0xf
	v_fmac_f32_dpp v249, v201, v145 row_ror:2 row_mask:0xf bank_mask:0xf
	v_fmac_f32_dpp v250, v204, v146 row_ror:2 row_mask:0xf bank_mask:0xf
	v_fmac_f32_dpp v251, v205, v147 row_ror:2 row_mask:0xf bank_mask:0xf
	s_and_saveexec_b64 s[0:1], s[12:13]
	global_store_dwordx4 v239, v[220:223], s[84:85]
	global_store_dwordx4 v241, v[248:251], s[84:85]
	s_or_b64 exec, exec, s[0:1]
	v_pk_mul_f32 v[224:225], v[220:221], s[100:101] op_sel_hi:[1,0]
	v_pk_mul_f32 v[190:191], v[222:223], s[100:101] op_sel_hi:[1,0]
	v_exp_f32_e32 v224, v224
	v_exp_f32_e32 v225, v225
	v_exp_f32_e32 v190, v190
	v_exp_f32_e32 v191, v191
	v_pk_mul_f32 v[220:221], v[220:221], v[248:249]
	v_pk_mul_f32 v[222:223], v[222:223], v[250:251]
	v_pk_add_f32 v[224:225], v[224:225], 1.0 op_sel_hi:[1,0]
	v_pk_add_f32 v[190:191], v[190:191], 1.0 op_sel_hi:[1,0]
	v_rcp_f32_e32 v224, v224
	v_rcp_f32_e32 v225, v225
	v_rcp_f32_e32 v190, v190
	v_rcp_f32_e32 v191, v191
	v_pk_mul_f32 v[220:221], v[220:221], v[224:225]
	v_pk_mul_f32 v[222:223], v[222:223], v[190:191]
	v_cvt_pk_bf16_f32 v186, v220, v221
	v_cvt_pk_bf16_f32 v187, v222, v223
	v_pk_mul_f32 v[116:117], v[116:117], v[228:229] op_sel_hi:[1,0]
	v_pk_mul_f32 v[118:119], v[118:119], v[228:229] op_sel_hi:[1,0]
	v_pk_mul_f32 v[112:113], v[112:113], v[228:229] op_sel_hi:[1,0]
	v_pk_mul_f32 v[114:115], v[114:115], v[228:229] op_sel_hi:[1,0]
	v_pk_fma_f32 v[220:221], v[136:137], v[116:117], v[140:141]
	v_pk_fma_f32 v[222:223], v[138:139], v[118:119], v[142:143]
	v_pk_fma_f32 v[248:249], v[152:153], v[112:113], v[156:157]
	v_pk_fma_f32 v[250:251], v[154:155], v[114:115], v[158:159]
	v_cndmask_b32_e64 v188, v116, v124, s[98:99]
	v_cndmask_b32_e64 v189, v117, v125, s[98:99]
	v_cndmask_b32_e64 v196, v118, v126, s[98:99]
	v_cndmask_b32_e64 v197, v119, v127, s[98:99]
	v_cndmask_b32_e64 v200, v112, v120, s[98:99]
	v_cndmask_b32_e64 v201, v113, v121, s[98:99]
	v_cndmask_b32_e64 v204, v114, v122, s[98:99]
	v_cndmask_b32_e64 v205, v115, v123, s[98:99]
	v_fmac_f32_dpp v220, v188, v132 row_ror:1 row_mask:0xf bank_mask:0xf
	v_fmac_f32_dpp v221, v189, v133 row_ror:1 row_mask:0xf bank_mask:0xf
	v_fmac_f32_dpp v222, v196, v134 row_ror:1 row_mask:0xf bank_mask:0xf
	v_fmac_f32_dpp v223, v197, v135 row_ror:1 row_mask:0xf bank_mask:0xf
	v_fmac_f32_dpp v248, v200, v148 row_ror:1 row_mask:0xf bank_mask:0xf
	v_fmac_f32_dpp v249, v201, v149 row_ror:1 row_mask:0xf bank_mask:0xf
	v_fmac_f32_dpp v250, v204, v150 row_ror:1 row_mask:0xf bank_mask:0xf
	v_fmac_f32_dpp v251, v205, v151 row_ror:1 row_mask:0xf bank_mask:0xf
	v_cndmask_b32_e64 v188, v124, v116, s[40:41]
	v_cndmask_b32_e64 v189, v125, v117, s[40:41]
	v_cndmask_b32_e64 v196, v126, v118, s[40:41]
	v_cndmask_b32_e64 v197, v127, v119, s[40:41]
	v_cndmask_b32_e64 v200, v120, v112, s[40:41]
	v_cndmask_b32_e64 v201, v121, v113, s[40:41]
	v_cndmask_b32_e64 v204, v122, v114, s[40:41]
	v_cndmask_b32_e64 v205, v123, v115, s[40:41]
	v_fmac_f32_dpp v220, v188, v128 row_ror:2 row_mask:0xf bank_mask:0xf
	v_fmac_f32_dpp v221, v189, v129 row_ror:2 row_mask:0xf bank_mask:0xf
	v_fmac_f32_dpp v222, v196, v130 row_ror:2 row_mask:0xf bank_mask:0xf
	v_fmac_f32_dpp v223, v197, v131 row_ror:2 row_mask:0xf bank_mask:0xf
	v_fmac_f32_dpp v248, v200, v144 row_ror:2 row_mask:0xf bank_mask:0xf
	v_fmac_f32_dpp v249, v201, v145 row_ror:2 row_mask:0xf bank_mask:0xf
	v_fmac_f32_dpp v250, v204, v146 row_ror:2 row_mask:0xf bank_mask:0xf
; __device__ __forceinline__ unsigned cvt_pk_bf16(float lo, float hi) { unsigned r; asm volatile("v_cvt_pk_bf16_f32 %0, %1, %2" : "=v"(r) : "v"(lo), "v"(hi)); return r; }
; __device__ __forceinline__ float dpp_ror1(float x) { return __int_as_float(__builtin_amdgcn_update_dpp(0, __float_as_int(x), 0x121, 0xf, 0xf, false)); }
; __device__ __forceinline__ float dpp_ror2(float x) { return __int_as_float(__builtin_amdgcn_update_dpp(0, __float_as_int(x), 0x122, 0xf, 0xf, false)); }
;     __device__ __forceinline__ void operator()(const f32x4 (&acc)[2][2][4][2], const Unit& u, int wr, int wc, int fr, int fq) const {
;     ...
;                 for (int m = 0; m < 4; ++m) {
;                     f32x4 cur[2], h[2];
; #pragma unroll
;                     for (int bj = 0; bj < 2; ++bj) { cur[bj] = acc[ai][bj][m][n] * rs[ai][m]; f32x4 x1, x2;
; #pragma unroll
;                         for (int e = 0; e < 4; ++e) { const float c1 = dpp_ror1(cur[bj][e]), p1 = dpp_ror1(pg[bj][e]), c2 = dpp_ror2(cur[bj][e]), p2 = dpp_ror2(pg[bj][e]);
;                             x1[e] = fr >= 1 ? c1 : p1; x2[e] = fr >= 2 ? c2 : p2; }
;                         h[bj] = bb[bj] + w0[bj] * x2 + w1[bj] * x1 + w2[bj] * cur[bj]; }
;                     if (ai == 0 && wr == 0 && m == 0 && fr < 2) {
;                         *(f32x4*)(hc0 + (size_t)(u.pm * 2 + fr) * FF2 + gcol + 4 * n) = h[0]; *(f32x4*)(hc0 + (size_t)(u.pm * 2 + fr) * FF2 + FF + gcol + 4 * n) = h[1]; }
;                     f32x4 a;
; #pragma unroll
;                     for (int e = 0; e < 4; ++e) { const float g = h[0][e]; a[e] = g * __builtin_amdgcn_rcpf(1.0f + __builtin_amdgcn_exp2f(-1.4426950408889634f * g)) * h[1][e]; }
;                     const unsigned p0 = cvt_pk_bf16(a[0], a[1]), p1 = cvt_pk_bf16(a[2], a[3]);
;                     if (n == 0) { pk_lo[ai][m][0] = p0; pk_lo[ai][m][1] = p1; }
	v_fmac_f32_dpp v251, v205, v147 row_ror:2 row_mask:0xf bank_mask:0xf
	v_pk_mul_f32 v[224:225], v[220:221], s[100:101] op_sel_hi:[1,0]
	v_pk_mul_f32 v[190:191], v[222:223], s[100:101] op_sel_hi:[1,0]
	v_exp_f32_e32 v224, v224
	v_exp_f32_e32 v225, v225
	v_exp_f32_e32 v190, v190
	v_exp_f32_e32 v191, v191
	v_pk_mul_f32 v[220:221], v[220:221], v[248:249]
	v_pk_mul_f32 v[222:223], v[222:223], v[250:251]
	v_pk_add_f32 v[224:225], v[224:225], 1.0 op_sel_hi:[1,0]
	v_pk_add_f32 v[190:191], v[190:191], 1.0 op_sel_hi:[1,0]
	v_rcp_f32_e32 v224, v224
	v_rcp_f32_e32 v225, v225
	v_rcp_f32_e32 v190, v190
	v_rcp_f32_e32 v191, v191
	v_pk_mul_f32 v[220:221], v[220:221], v[224:225]
	v_pk_mul_f32 v[222:223], v[222:223], v[190:191]
	v_cvt_pk_bf16_f32 v194, v220, v221
	v_cvt_pk_bf16_f32 v195, v222, v223
	v_pk_mul_f32 v[108:109], v[108:109], v[230:231] op_sel_hi:[1,0]
	v_pk_mul_f32 v[110:111], v[110:111], v[230:231] op_sel_hi:[1,0]
	v_pk_mul_f32 v[104:105], v[104:105], v[230:231] op_sel_hi:[1,0]
	v_pk_mul_f32 v[106:107], v[106:107], v[230:231] op_sel_hi:[1,0]
	v_pk_fma_f32 v[220:221], v[136:137], v[108:109], v[140:141]
	v_pk_fma_f32 v[222:223], v[138:139], v[110:111], v[142:143]
	v_pk_fma_f32 v[248:249], v[152:153], v[104:105], v[156:157]
	v_pk_fma_f32 v[250:251], v[154:155], v[106:107], v[158:159]
	v_cndmask_b32_e64 v188, v108, v116, s[98:99]
	v_cndmask_b32_e64 v189, v109, v117, s[98:99]
	v_cndmask_b32_e64 v196, v110, v118, s[98:99]
	v_cndmask_b32_e64 v197, v111, v119, s[98:99]
	v_cndmask_b32_e64 v200, v104, v112, s[98:99]
	v_cndmask_b32_e64 v201, v105, v113, s[98:99]
	v_cndmask_b32_e64 v204, v106, v114, s[98:99]
	v_cndmask_b32_e64 v205, v107, v115, s[98:99]
	v_fmac_f32_dpp v220, v188, v132 row_ror:1 row_mask:0xf bank_mask:0xf
	v_fmac_f32_dpp v221, v189, v133 row_ror:1 row_mask:0xf bank_mask:0xf
	v_fmac_f32_dpp v222, v196, v134 row_ror:1 row_mask:0xf bank_mask:0xf
	v_fmac_f32_dpp v223, v197, v135 row_ror:1 row_mask:0xf bank_mask:0xf
	v_fmac_f32_dpp v248, v200, v148 row_ror:1 row_mask:0xf bank_mask:0xf
	v_fmac_f32_dpp v249, v201, v149 row_ror:1 row_mask:0xf bank_mask:0xf
	v_fmac_f32_dpp v250, v204, v150 row_ror:1 row_mask:0xf bank_mask:0xf
	v_fmac_f32_dpp v251, v205, v151 row_ror:1 row_mask:0xf bank_mask:0xf
	v_cndmask_b32_e64 v188, v116, v108, s[40:41]
	v_cndmask_b32_e64 v189, v117, v109, s[40:41]
	v_cndmask_b32_e64 v196, v118, v110, s[40:41]
	v_cndmask_b32_e64 v197, v119, v111, s[40:41]
	v_cndmask_b32_e64 v200, v112, v104, s[40:41]
	v_cndmask_b32_e64 v201, v113, v105, s[40:41]
	v_cndmask_b32_e64 v204, v114, v106, s[40:41]
	v_cndmask_b32_e64 v205, v115, v107, s[40:41]
	v_fmac_f32_dpp v220, v188, v128 row_ror:2 row_mask:0xf bank_mask:0xf
	v_fmac_f32_dpp v221, v189, v129 row_ror:2 row_mask:0xf bank_mask:0xf
	v_fmac_f32_dpp v222, v196, v130 row_ror:2 row_mask:0xf bank_mask:0xf
	v_fmac_f32_dpp v223, v197, v131 row_ror:2 row_mask:0xf bank_mask:0xf
	v_fmac_f32_dpp v248, v200, v144 row_ror:2 row_mask:0xf bank_mask:0xf
	v_fmac_f32_dpp v249, v201, v145 row_ror:2 row_mask:0xf bank_mask:0xf
	v_fmac_f32_dpp v250, v204, v146 row_ror:2 row_mask:0xf bank_mask:0xf
	v_fmac_f32_dpp v251, v205, v147 row_ror:2 row_mask:0xf bank_mask:0xf
	v_pk_mul_f32 v[224:225], v[220:221], s[100:101] op_sel_hi:[1,0]
	v_pk_mul_f32 v[190:191], v[222:223], s[100:101] op_sel_hi:[1,0]
	v_exp_f32_e32 v224, v224
	v_exp_f32_e32 v225, v225
	v_exp_f32_e32 v190, v190
	v_exp_f32_e32 v191, v191
	v_pk_mul_f32 v[220:221], v[220:221], v[248:249]
	v_pk_mul_f32 v[222:223], v[222:223], v[250:251]
	v_pk_add_f32 v[224:225], v[224:225], 1.0 op_sel_hi:[1,0]
	v_pk_add_f32 v[190:191], v[190:191], 1.0 op_sel_hi:[1,0]
	v_rcp_f32_e32 v224, v224
	v_rcp_f32_e32 v225, v225
	v_rcp_f32_e32 v190, v190
	v_rcp_f32_e32 v191, v191
	v_pk_mul_f32 v[220:221], v[220:221], v[224:225]
	v_pk_mul_f32 v[222:223], v[222:223], v[190:191]
	v_cvt_pk_bf16_f32 v198, v220, v221
	v_cvt_pk_bf16_f32 v199, v222, v223
	v_pk_fma_f32 v[220:221], v[136:137], v[100:101], v[140:141]
	v_pk_fma_f32 v[222:223], v[138:139], v[102:103], v[142:143]
	v_pk_fma_f32 v[248:249], v[152:153], v[96:97], v[156:157]
	v_pk_fma_f32 v[250:251], v[154:155], v[98:99], v[158:159]
	v_cndmask_b32_e64 v188, v100, v108, s[98:99]
	v_cndmask_b32_e64 v189, v101, v109, s[98:99]
	v_cndmask_b32_e64 v196, v102, v110, s[98:99]
	v_cndmask_b32_e64 v197, v103, v111, s[98:99]
	v_cndmask_b32_e64 v200, v96, v104, s[98:99]
	v_cndmask_b32_e64 v201, v97, v105, s[98:99]
	v_cndmask_b32_e64 v204, v98, v106, s[98:99]
	v_cndmask_b32_e64 v205, v99, v107, s[98:99]
	v_fmac_f32_dpp v220, v188, v132 row_ror:1 row_mask:0xf bank_mask:0xf
	v_fmac_f32_dpp v221, v189, v133 row_ror:1 row_mask:0xf bank_mask:0xf
	v_fmac_f32_dpp v222, v196, v134 row_ror:1 row_mask:0xf bank_mask:0xf
	v_fmac_f32_dpp v223, v197, v135 row_ror:1 row_mask:0xf bank_mask:0xf
	v_fmac_f32_dpp v248, v200, v148 row_ror:1 row_mask:0xf bank_mask:0xf
	v_fmac_f32_dpp v249, v201, v149 row_ror:1 row_mask:0xf bank_mask:0xf
	v_fmac_f32_dpp v250, v204, v150 row_ror:1 row_mask:0xf bank_mask:0xf
	v_fmac_f32_dpp v251, v205, v151 row_ror:1 row_mask:0xf bank_mask:0xf
	v_cndmask_b32_e64 v188, v108, v100, s[40:41]
	v_cndmask_b32_e64 v189, v109, v101, s[40:41]
	v_cndmask_b32_e64 v196, v110, v102, s[40:41]
	v_cndmask_b32_e64 v197, v111, v103, s[40:41]
	v_cndmask_b32_e64 v200, v104, v96, s[40:41]
	v_cndmask_b32_e64 v201, v105, v97, s[40:41]
	v_cndmask_b32_e64 v204, v106, v98, s[40:41]
	v_cndmask_b32_e64 v205, v107, v99, s[40:41]
	v_fmac_f32_dpp v220, v188, v128 row_ror:2 row_mask:0xf bank_mask:0xf
	v_fmac_f32_dpp v221, v189, v129 row_ror:2 row_mask:0xf bank_mask:0xf
	v_fmac_f32_dpp v222, v196, v130 row_ror:2 row_mask:0xf bank_mask:0xf
; #define PG8_LAS __attribute__((address_space(3)))
; __device__ __forceinline__ unsigned cvt_pk_bf16(float lo, float hi) { unsigned r; asm volatile("v_cvt_pk_bf16_f32 %0, %1, %2" : "=v"(r) : "v"(lo), "v"(hi)); return r; }
;     __device__ __forceinline__ void operator()(const f32x4 (&acc)[2][2][4][2], const Unit& u, int wr, int wc, int fr, int fq) const {
;     ...
;             if (n == 1) {
; #pragma unroll
;                 for (int bj = 0; bj < 2; ++bj) { const int col = bj * FF + gcol + 4;
;                     w0[bj] = *(const f32x4*)(cw + col); w1[bj] = *(const f32x4*)(cw + FF2 + col); w2[bj] = *(const f32x4*)(cw + 2 * FF2 + col); bb[bj] = *(const f32x4*)(cb + col); } }
; #pragma unroll
;             for (int ai = 0; ai < 2; ++ai) {
;                 f32x4 pg[2]; const int pb = ai * 2 + wr - 1;
; #pragma unroll
;                 for (int bj = 0; bj < 2; ++bj) { pg[bj] = (f32x4){0.f, 0.f, 0.f, 0.f};
;                     if (pb >= 0 && fr >= 14) pg[bj] = *(const PG8_LAS f32x4*)(halo + (pb * 2 + (fr - 14)) * 256 + bj * HALF + lcol + 4 * n); }
; #pragma unroll
;                 for (int m = 0; m < 4; ++m) {
;                     f32x4 cur[2], h[2];
; #pragma unroll
;                     for (int bj = 0; bj < 2; ++bj) { cur[bj] = acc[ai][bj][m][n] * rs[ai][m]; f32x4 x1, x2;
; #pragma unroll
;                         for (int e = 0; e < 4; ++e) { const float c1 = dpp_ror1(cur[bj][e]), p1 = dpp_ror1(pg[bj][e]), c2 = dpp_ror2(cur[bj][e]), p2 = dpp_ror2(pg[bj][e]);
;                             x1[e] = fr >= 1 ? c1 : p1; x2[e] = fr >= 2 ? c2 : p2; }
;                         h[bj] = bb[bj] + w0[bj] * x2 + w1[bj] * x1 + w2[bj] * cur[bj]; }
;                     if (ai == 0 && wr == 0 && m == 0 && fr < 2) {
;                         *(f32x4*)(hc0 + (size_t)(u.pm * 2 + fr) * FF2 + gcol + 4 * n) = h[0]; *(f32x4*)(hc0 + (size_t)(u.pm * 2 + fr) * FF2 + FF + gcol + 4 * n) = h[1]; }
;                     f32x4 a;
; #pragma unroll
;                     for (int e = 0; e < 4; ++e) { const float g = h[0][e]; a[e] = g * __builtin_amdgcn_rcpf(1.0f + __builtin_amdgcn_exp2f(-1.4426950408889634f * g)) * h[1][e]; }
;                     const unsigned p0 = cvt_pk_bf16(a[0], a[1]), p1 = cvt_pk_bf16(a[2], a[3]);
;                     if (n == 0) { pk_lo[ai][m][0] = p0; pk_lo[ai][m][1] = p1; }
	v_fmac_f32_dpp v223, v197, v131 row_ror:2 row_mask:0xf bank_mask:0xf
	v_fmac_f32_dpp v248, v200, v144 row_ror:2 row_mask:0xf bank_mask:0xf
	v_fmac_f32_dpp v249, v201, v145 row_ror:2 row_mask:0xf bank_mask:0xf
	v_fmac_f32_dpp v250, v204, v146 row_ror:2 row_mask:0xf bank_mask:0xf
	v_fmac_f32_dpp v251, v205, v147 row_ror:2 row_mask:0xf bank_mask:0xf
	v_pk_mul_f32 v[224:225], v[220:221], s[100:101] op_sel_hi:[1,0]
	v_pk_mul_f32 v[190:191], v[222:223], s[100:101] op_sel_hi:[1,0]
	v_exp_f32_e32 v224, v224
	v_exp_f32_e32 v225, v225
	v_exp_f32_e32 v190, v190
	v_exp_f32_e32 v191, v191
	v_pk_mul_f32 v[220:221], v[220:221], v[248:249]
	v_pk_mul_f32 v[222:223], v[222:223], v[250:251]
	v_pk_add_f32 v[224:225], v[224:225], 1.0 op_sel_hi:[1,0]
	v_pk_add_f32 v[190:191], v[190:191], 1.0 op_sel_hi:[1,0]
	v_rcp_f32_e32 v224, v224
	v_rcp_f32_e32 v225, v225
	v_rcp_f32_e32 v190, v190
	v_rcp_f32_e32 v191, v191
	v_pk_mul_f32 v[220:221], v[220:221], v[224:225]
	v_pk_mul_f32 v[222:223], v[222:223], v[190:191]
	v_cvt_pk_bf16_f32 v202, v220, v221
	v_cvt_pk_bf16_f32 v203, v222, v223
	global_load_dwordx4 v[124:127], v231, s[14:15] offset:16
	global_load_dwordx4 v[116:119], v231, s[16:17] offset:16
	global_load_dwordx4 v[108:111], v231, s[92:93] offset:16
	global_load_dwordx4 v[100:103], v231, s[60:61] offset:16
	global_load_dwordx4 v[120:123], v233, s[14:15] offset:16
	global_load_dwordx4 v[112:115], v233, s[16:17] offset:16
	global_load_dwordx4 v[104:107], v233, s[92:93] offset:16
	global_load_dwordx4 v[96:99], v233, s[60:61] offset:16
	v_pk_mul_f32 v[92:93], v[92:93], v[234:235] op_sel_hi:[1,0]
	v_pk_mul_f32 v[94:95], v[94:95], v[234:235] op_sel_hi:[1,0]
	v_pk_mul_f32 v[88:89], v[88:89], v[234:235] op_sel_hi:[1,0]
	v_pk_mul_f32 v[90:91], v[90:91], v[234:235] op_sel_hi:[1,0]
	v_pk_fma_f32 v[220:221], v[136:137], v[92:93], v[140:141]
	v_pk_fma_f32 v[222:223], v[138:139], v[94:95], v[142:143]
	v_pk_fma_f32 v[248:249], v[152:153], v[88:89], v[156:157]
	v_pk_fma_f32 v[250:251], v[154:155], v[90:91], v[158:159]
	v_cndmask_b32_e64 v188, v92, v178, s[98:99]
	v_cndmask_b32_e64 v189, v93, v179, s[98:99]
	v_cndmask_b32_e64 v196, v94, v180, s[98:99]
	v_cndmask_b32_e64 v197, v95, v181, s[98:99]
	v_cndmask_b32_e64 v200, v88, v182, s[98:99]
	v_cndmask_b32_e64 v201, v89, v183, s[98:99]
	v_cndmask_b32_e64 v204, v90, v184, s[98:99]
	v_cndmask_b32_e64 v205, v91, v185, s[98:99]
	v_fmac_f32_dpp v220, v188, v132 row_ror:1 row_mask:0xf bank_mask:0xf
	v_fmac_f32_dpp v221, v189, v133 row_ror:1 row_mask:0xf bank_mask:0xf
	v_fmac_f32_dpp v222, v196, v134 row_ror:1 row_mask:0xf bank_mask:0xf
	v_fmac_f32_dpp v223, v197, v135 row_ror:1 row_mask:0xf bank_mask:0xf
	v_fmac_f32_dpp v248, v200, v148 row_ror:1 row_mask:0xf bank_mask:0xf
	v_fmac_f32_dpp v249, v201, v149 row_ror:1 row_mask:0xf bank_mask:0xf
	v_fmac_f32_dpp v250, v204, v150 row_ror:1 row_mask:0xf bank_mask:0xf
	v_fmac_f32_dpp v251, v205, v151 row_ror:1 row_mask:0xf bank_mask:0xf
	v_cndmask_b32_e64 v188, v178, v92, s[40:41]
	v_cndmask_b32_e64 v189, v179, v93, s[40:41]
	v_cndmask_b32_e64 v196, v180, v94, s[40:41]
	v_cndmask_b32_e64 v197, v181, v95, s[40:41]
	v_cndmask_b32_e64 v200, v182, v88, s[40:41]
	v_cndmask_b32_e64 v201, v183, v89, s[40:41]
	v_cndmask_b32_e64 v204, v184, v90, s[40:41]
	v_cndmask_b32_e64 v205, v185, v91, s[40:41]
	v_fmac_f32_dpp v220, v188, v128 row_ror:2 row_mask:0xf bank_mask:0xf
	v_fmac_f32_dpp v221, v189, v129 row_ror:2 row_mask:0xf bank_mask:0xf
	v_fmac_f32_dpp v222, v196, v130 row_ror:2 row_mask:0xf bank_mask:0xf
	v_fmac_f32_dpp v223, v197, v131 row_ror:2 row_mask:0xf bank_mask:0xf
	v_fmac_f32_dpp v248, v200, v144 row_ror:2 row_mask:0xf bank_mask:0xf
	v_fmac_f32_dpp v249, v201, v145 row_ror:2 row_mask:0xf bank_mask:0xf
	v_fmac_f32_dpp v250, v204, v146 row_ror:2 row_mask:0xf bank_mask:0xf
	v_fmac_f32_dpp v251, v205, v147 row_ror:2 row_mask:0xf bank_mask:0xf
	v_pk_mul_f32 v[224:225], v[220:221], s[100:101] op_sel_hi:[1,0]
	v_pk_mul_f32 v[190:191], v[222:223], s[100:101] op_sel_hi:[1,0]
	v_exp_f32_e32 v224, v224
	v_exp_f32_e32 v225, v225
	v_exp_f32_e32 v190, v190
	v_exp_f32_e32 v191, v191
	v_pk_mul_f32 v[220:221], v[220:221], v[248:249]
	v_pk_mul_f32 v[222:223], v[222:223], v[250:251]
	v_pk_add_f32 v[224:225], v[224:225], 1.0 op_sel_hi:[1,0]
	v_pk_add_f32 v[190:191], v[190:191], 1.0 op_sel_hi:[1,0]
	v_rcp_f32_e32 v224, v224
	v_rcp_f32_e32 v225, v225
	v_rcp_f32_e32 v190, v190
	v_rcp_f32_e32 v191, v191
	v_pk_mul_f32 v[220:221], v[220:221], v[224:225]
	v_pk_mul_f32 v[222:223], v[222:223], v[190:191]
	v_cvt_pk_bf16_f32 v160, v220, v221
	v_cvt_pk_bf16_f32 v161, v222, v223
	v_pk_mul_f32 v[84:85], v[84:85], v[236:237] op_sel_hi:[1,0]
	v_pk_mul_f32 v[86:87], v[86:87], v[236:237] op_sel_hi:[1,0]
	v_pk_mul_f32 v[80:81], v[80:81], v[236:237] op_sel_hi:[1,0]
	v_pk_mul_f32 v[82:83], v[82:83], v[236:237] op_sel_hi:[1,0]
	v_pk_fma_f32 v[220:221], v[136:137], v[84:85], v[140:141]
	v_pk_fma_f32 v[222:223], v[138:139], v[86:87], v[142:143]
	v_pk_fma_f32 v[248:249], v[152:153], v[80:81], v[156:157]
	v_pk_fma_f32 v[250:251], v[154:155], v[82:83], v[158:159]
	v_cndmask_b32_e64 v188, v84, v92, s[98:99]
	v_cndmask_b32_e64 v189, v85, v93, s[98:99]
	v_cndmask_b32_e64 v196, v86, v94, s[98:99]
	v_cndmask_b32_e64 v197, v87, v95, s[98:99]
	v_cndmask_b32_e64 v200, v80, v88, s[98:99]
	v_cndmask_b32_e64 v201, v81, v89, s[98:99]
	v_cndmask_b32_e64 v204, v82, v90, s[98:99]
; __device__ __forceinline__ unsigned cvt_pk_bf16(float lo, float hi) { unsigned r; asm volatile("v_cvt_pk_bf16_f32 %0, %1, %2" : "=v"(r) : "v"(lo), "v"(hi)); return r; }
; __device__ __forceinline__ float dpp_ror1(float x) { return __int_as_float(__builtin_amdgcn_update_dpp(0, __float_as_int(x), 0x121, 0xf, 0xf, false)); }
; __device__ __forceinline__ float dpp_ror2(float x) { return __int_as_float(__builtin_amdgcn_update_dpp(0, __float_as_int(x), 0x122, 0xf, 0xf, false)); }
;     __device__ __forceinline__ void operator()(const f32x4 (&acc)[2][2][4][2], const Unit& u, int wr, int wc, int fr, int fq) const {
;     ...
;                 for (int m = 0; m < 4; ++m) {
;                     f32x4 cur[2], h[2];
; #pragma unroll
;                     for (int bj = 0; bj < 2; ++bj) { cur[bj] = acc[ai][bj][m][n] * rs[ai][m]; f32x4 x1, x2;
; #pragma unroll
;                         for (int e = 0; e < 4; ++e) { const float c1 = dpp_ror1(cur[bj][e]), p1 = dpp_ror1(pg[bj][e]), c2 = dpp_ror2(cur[bj][e]), p2 = dpp_ror2(pg[bj][e]);
;                             x1[e] = fr >= 1 ? c1 : p1; x2[e] = fr >= 2 ? c2 : p2; }
;                         h[bj] = bb[bj] + w0[bj] * x2 + w1[bj] * x1 + w2[bj] * cur[bj]; }
;                     if (ai == 0 && wr == 0 && m == 0 && fr < 2) {
;                         *(f32x4*)(hc0 + (size_t)(u.pm * 2 + fr) * FF2 + gcol + 4 * n) = h[0]; *(f32x4*)(hc0 + (size_t)(u.pm * 2 + fr) * FF2 + FF + gcol + 4 * n) = h[1]; }
;                     f32x4 a;
; #pragma unroll
;                     for (int e = 0; e < 4; ++e) { const float g = h[0][e]; a[e] = g * __builtin_amdgcn_rcpf(1.0f + __builtin_amdgcn_exp2f(-1.4426950408889634f * g)) * h[1][e]; }
;                     const unsigned p0 = cvt_pk_bf16(a[0], a[1]), p1 = cvt_pk_bf16(a[2], a[3]);
;                     if (n == 0) { pk_lo[ai][m][0] = p0; pk_lo[ai][m][1] = p1; }
	v_cndmask_b32_e64 v205, v83, v91, s[98:99]
	v_fmac_f32_dpp v220, v188, v132 row_ror:1 row_mask:0xf bank_mask:0xf
	v_fmac_f32_dpp v221, v189, v133 row_ror:1 row_mask:0xf bank_mask:0xf
	v_fmac_f32_dpp v222, v196, v134 row_ror:1 row_mask:0xf bank_mask:0xf
	v_fmac_f32_dpp v223, v197, v135 row_ror:1 row_mask:0xf bank_mask:0xf
	v_fmac_f32_dpp v248, v200, v148 row_ror:1 row_mask:0xf bank_mask:0xf
	v_fmac_f32_dpp v249, v201, v149 row_ror:1 row_mask:0xf bank_mask:0xf
	v_fmac_f32_dpp v250, v204, v150 row_ror:1 row_mask:0xf bank_mask:0xf
	v_fmac_f32_dpp v251, v205, v151 row_ror:1 row_mask:0xf bank_mask:0xf
	v_cndmask_b32_e64 v188, v92, v84, s[40:41]
	v_cndmask_b32_e64 v189, v93, v85, s[40:41]
	v_cndmask_b32_e64 v196, v94, v86, s[40:41]
	v_cndmask_b32_e64 v197, v95, v87, s[40:41]
	v_cndmask_b32_e64 v200, v88, v80, s[40:41]
	v_cndmask_b32_e64 v201, v89, v81, s[40:41]
	v_cndmask_b32_e64 v204, v90, v82, s[40:41]
	v_cndmask_b32_e64 v205, v91, v83, s[40:41]
	v_fmac_f32_dpp v220, v188, v128 row_ror:2 row_mask:0xf bank_mask:0xf
	v_fmac_f32_dpp v221, v189, v129 row_ror:2 row_mask:0xf bank_mask:0xf
	v_fmac_f32_dpp v222, v196, v130 row_ror:2 row_mask:0xf bank_mask:0xf
	v_fmac_f32_dpp v223, v197, v131 row_ror:2 row_mask:0xf bank_mask:0xf
	v_fmac_f32_dpp v248, v200, v144 row_ror:2 row_mask:0xf bank_mask:0xf
	v_fmac_f32_dpp v249, v201, v145 row_ror:2 row_mask:0xf bank_mask:0xf
	v_fmac_f32_dpp v250, v204, v146 row_ror:2 row_mask:0xf bank_mask:0xf
	v_fmac_f32_dpp v251, v205, v147 row_ror:2 row_mask:0xf bank_mask:0xf
	v_pk_mul_f32 v[224:225], v[220:221], s[100:101] op_sel_hi:[1,0]
	v_pk_mul_f32 v[190:191], v[222:223], s[100:101] op_sel_hi:[1,0]
	v_exp_f32_e32 v224, v224
	v_exp_f32_e32 v225, v225
	v_exp_f32_e32 v190, v190
	v_exp_f32_e32 v191, v191
	v_pk_mul_f32 v[220:221], v[220:221], v[248:249]
	v_pk_mul_f32 v[222:223], v[222:223], v[250:251]
	v_pk_add_f32 v[224:225], v[224:225], 1.0 op_sel_hi:[1,0]
	v_pk_add_f32 v[190:191], v[190:191], 1.0 op_sel_hi:[1,0]
	v_rcp_f32_e32 v224, v224
	v_rcp_f32_e32 v225, v225
	v_rcp_f32_e32 v190, v190
	v_rcp_f32_e32 v191, v191
	v_pk_mul_f32 v[220:221], v[220:221], v[224:225]
	v_pk_mul_f32 v[222:223], v[222:223], v[190:191]
	v_cvt_pk_bf16_f32 v164, v220, v221
	v_cvt_pk_bf16_f32 v165, v222, v223
	v_pk_mul_f32 v[76:77], v[76:77], v[238:239] op_sel_hi:[1,0]
	v_pk_mul_f32 v[78:79], v[78:79], v[238:239] op_sel_hi:[1,0]
	v_pk_mul_f32 v[72:73], v[72:73], v[238:239] op_sel_hi:[1,0]
	v_pk_mul_f32 v[74:75], v[74:75], v[238:239] op_sel_hi:[1,0]
	v_pk_fma_f32 v[220:221], v[136:137], v[76:77], v[140:141]
	v_pk_fma_f32 v[222:223], v[138:139], v[78:79], v[142:143]
	v_pk_fma_f32 v[248:249], v[152:153], v[72:73], v[156:157]
	v_pk_fma_f32 v[250:251], v[154:155], v[74:75], v[158:159]
	v_cndmask_b32_e64 v188, v76, v84, s[98:99]
	v_cndmask_b32_e64 v189, v77, v85, s[98:99]
	v_cndmask_b32_e64 v196, v78, v86, s[98:99]
	v_cndmask_b32_e64 v197, v79, v87, s[98:99]
	v_cndmask_b32_e64 v200, v72, v80, s[98:99]
	v_cndmask_b32_e64 v201, v73, v81, s[98:99]
	v_cndmask_b32_e64 v204, v74, v82, s[98:99]
	v_cndmask_b32_e64 v205, v75, v83, s[98:99]
	v_fmac_f32_dpp v220, v188, v132 row_ror:1 row_mask:0xf bank_mask:0xf
	v_fmac_f32_dpp v221, v189, v133 row_ror:1 row_mask:0xf bank_mask:0xf
	v_fmac_f32_dpp v222, v196, v134 row_ror:1 row_mask:0xf bank_mask:0xf
	v_fmac_f32_dpp v223, v197, v135 row_ror:1 row_mask:0xf bank_mask:0xf
	v_fmac_f32_dpp v248, v200, v148 row_ror:1 row_mask:0xf bank_mask:0xf
	v_fmac_f32_dpp v249, v201, v149 row_ror:1 row_mask:0xf bank_mask:0xf
	v_fmac_f32_dpp v250, v204, v150 row_ror:1 row_mask:0xf bank_mask:0xf
	v_fmac_f32_dpp v251, v205, v151 row_ror:1 row_mask:0xf bank_mask:0xf
	v_cndmask_b32_e64 v188, v84, v76, s[40:41]
	v_cndmask_b32_e64 v189, v85, v77, s[40:41]
	v_cndmask_b32_e64 v196, v86, v78, s[40:41]
	v_cndmask_b32_e64 v197, v87, v79, s[40:41]
	v_cndmask_b32_e64 v200, v80, v72, s[40:41]
	v_cndmask_b32_e64 v201, v81, v73, s[40:41]
	v_cndmask_b32_e64 v204, v82, v74, s[40:41]
	v_cndmask_b32_e64 v205, v83, v75, s[40:41]
	v_fmac_f32_dpp v220, v188, v128 row_ror:2 row_mask:0xf bank_mask:0xf
	v_fmac_f32_dpp v221, v189, v129 row_ror:2 row_mask:0xf bank_mask:0xf
	v_fmac_f32_dpp v222, v196, v130 row_ror:2 row_mask:0xf bank_mask:0xf
	v_fmac_f32_dpp v223, v197, v131 row_ror:2 row_mask:0xf bank_mask:0xf
	v_fmac_f32_dpp v248, v200, v144 row_ror:2 row_mask:0xf bank_mask:0xf
	v_fmac_f32_dpp v249, v201, v145 row_ror:2 row_mask:0xf bank_mask:0xf
	v_fmac_f32_dpp v250, v204, v146 row_ror:2 row_mask:0xf bank_mask:0xf
	v_fmac_f32_dpp v251, v205, v147 row_ror:2 row_mask:0xf bank_mask:0xf
	v_pk_mul_f32 v[224:225], v[220:221], s[100:101] op_sel_hi:[1,0]
	v_pk_mul_f32 v[190:191], v[222:223], s[100:101] op_sel_hi:[1,0]
	v_exp_f32_e32 v224, v224
	v_exp_f32_e32 v225, v225
	v_exp_f32_e32 v190, v190
	v_exp_f32_e32 v191, v191
	v_pk_mul_f32 v[220:221], v[220:221], v[248:249]
	v_pk_mul_f32 v[222:223], v[222:223], v[250:251]
	v_pk_add_f32 v[224:225], v[224:225], 1.0 op_sel_hi:[1,0]
	v_pk_add_f32 v[190:191], v[190:191], 1.0 op_sel_hi:[1,0]
	v_rcp_f32_e32 v224, v224
	v_rcp_f32_e32 v225, v225
	v_rcp_f32_e32 v190, v190
	v_rcp_f32_e32 v191, v191
	v_pk_mul_f32 v[220:221], v[220:221], v[224:225]
	v_pk_mul_f32 v[222:223], v[222:223], v[190:191]
	v_cvt_pk_bf16_f32 v178, v220, v221
	v_cvt_pk_bf16_f32 v179, v222, v223
	s_and_b64 vcc, exec, s[94:95]
	s_cbranch_vccnz .Lp7_hz1
	ds_read_b128 v[92:95], v215
	ds_read_b128 v[88:91], v216
	s_branch .Lp7_hr1

; #define PG8_LAS __attribute__((address_space(3)))
; __device__ __forceinline__ unsigned cvt_pk_bf16(float lo, float hi) { unsigned r; asm volatile("v_cvt_pk_bf16_f32 %0, %1, %2" : "=v"(r) : "v"(lo), "v"(hi)); return r; }
;     __device__ __forceinline__ void operator()(const f32x4 (&acc)[2][2][4][2], const Unit& u, int wr, int wc, int fr, int fq) const {
;     ...
;             for (int ai = 0; ai < 2; ++ai) {
;                 f32x4 pg[2]; const int pb = ai * 2 + wr - 1;
; #pragma unroll
;                 for (int bj = 0; bj < 2; ++bj) { pg[bj] = (f32x4){0.f, 0.f, 0.f, 0.f};
;                     if (pb >= 0 && fr >= 14) pg[bj] = *(const PG8_LAS f32x4*)(halo + (pb * 2 + (fr - 14)) * 256 + bj * HALF + lcol + 4 * n); }
; #pragma unroll
;                 for (int m = 0; m < 4; ++m) {
;                     f32x4 cur[2], h[2];
; #pragma unroll
;                     for (int bj = 0; bj < 2; ++bj) { cur[bj] = acc[ai][bj][m][n] * rs[ai][m]; f32x4 x1, x2;
; #pragma unroll
;                         for (int e = 0; e < 4; ++e) { const float c1 = dpp_ror1(cur[bj][e]), p1 = dpp_ror1(pg[bj][e]), c2 = dpp_ror2(cur[bj][e]), p2 = dpp_ror2(pg[bj][e]);
;                             x1[e] = fr >= 1 ? c1 : p1; x2[e] = fr >= 2 ? c2 : p2; }
;                         h[bj] = bb[bj] + w0[bj] * x2 + w1[bj] * x1 + w2[bj] * cur[bj]; }
;                     if (ai == 0 && wr == 0 && m == 0 && fr < 2) {
;                         *(f32x4*)(hc0 + (size_t)(u.pm * 2 + fr) * FF2 + gcol + 4 * n) = h[0]; *(f32x4*)(hc0 + (size_t)(u.pm * 2 + fr) * FF2 + FF + gcol + 4 * n) = h[1]; }
;                     f32x4 a;
; #pragma unroll
;                     for (int e = 0; e < 4; ++e) { const float g = h[0][e]; a[e] = g * __builtin_amdgcn_rcpf(1.0f + __builtin_amdgcn_exp2f(-1.4426950408889634f * g)) * h[1][e]; }
;                     const unsigned p0 = cvt_pk_bf16(a[0], a[1]), p1 = cvt_pk_bf16(a[2], a[3]);
;                     if (n == 0) { pk_lo[ai][m][0] = p0; pk_lo[ai][m][1] = p1; }
;                     else { u32x4 w; w.x = pk_lo[ai][m][0]; w.y = pk_lo[ai][m][1]; w.z = p0; w.w = p1;
;                         *(u32x4*)(act + (size_t)(u.pm * BM + ai * HALF + wr * 64 + m * 16 + fr) * FF + gcol) = w; }
;                     pg[0] = cur[0]; pg[1] = cur[1];
.Lp7_hr1:
	ds_read_b128 v[84:87], v217
	ds_read_b128 v[80:83], v218
	v_pk_fma_f32 v[220:221], v[136:137], v[68:69], v[140:141]
	v_pk_fma_f32 v[222:223], v[138:139], v[70:71], v[142:143]
	v_pk_fma_f32 v[248:249], v[152:153], v[64:65], v[156:157]
	v_pk_fma_f32 v[250:251], v[154:155], v[66:67], v[158:159]
	v_cndmask_b32_e64 v188, v68, v76, s[98:99]
	v_cndmask_b32_e64 v189, v69, v77, s[98:99]
	v_cndmask_b32_e64 v196, v70, v78, s[98:99]
	v_cndmask_b32_e64 v197, v71, v79, s[98:99]
	v_cndmask_b32_e64 v200, v64, v72, s[98:99]
	v_cndmask_b32_e64 v201, v65, v73, s[98:99]
	v_cndmask_b32_e64 v204, v66, v74, s[98:99]
	v_cndmask_b32_e64 v205, v67, v75, s[98:99]
	v_fmac_f32_dpp v220, v188, v132 row_ror:1 row_mask:0xf bank_mask:0xf
	v_fmac_f32_dpp v221, v189, v133 row_ror:1 row_mask:0xf bank_mask:0xf
	v_fmac_f32_dpp v222, v196, v134 row_ror:1 row_mask:0xf bank_mask:0xf
	v_fmac_f32_dpp v223, v197, v135 row_ror:1 row_mask:0xf bank_mask:0xf
	v_fmac_f32_dpp v248, v200, v148 row_ror:1 row_mask:0xf bank_mask:0xf
	v_fmac_f32_dpp v249, v201, v149 row_ror:1 row_mask:0xf bank_mask:0xf
	v_fmac_f32_dpp v250, v204, v150 row_ror:1 row_mask:0xf bank_mask:0xf
	v_fmac_f32_dpp v251, v205, v151 row_ror:1 row_mask:0xf bank_mask:0xf
	v_cndmask_b32_e64 v188, v76, v68, s[40:41]
	v_cndmask_b32_e64 v189, v77, v69, s[40:41]
	v_cndmask_b32_e64 v196, v78, v70, s[40:41]
	v_cndmask_b32_e64 v197, v79, v71, s[40:41]
	v_cndmask_b32_e64 v200, v72, v64, s[40:41]
	v_cndmask_b32_e64 v201, v73, v65, s[40:41]
	v_cndmask_b32_e64 v204, v74, v66, s[40:41]
	v_cndmask_b32_e64 v205, v75, v67, s[40:41]
	v_fmac_f32_dpp v220, v188, v128 row_ror:2 row_mask:0xf bank_mask:0xf
	v_fmac_f32_dpp v221, v189, v129 row_ror:2 row_mask:0xf bank_mask:0xf
	v_fmac_f32_dpp v222, v196, v130 row_ror:2 row_mask:0xf bank_mask:0xf
	v_fmac_f32_dpp v223, v197, v131 row_ror:2 row_mask:0xf bank_mask:0xf
	v_fmac_f32_dpp v248, v200, v144 row_ror:2 row_mask:0xf bank_mask:0xf
	v_fmac_f32_dpp v249, v201, v145 row_ror:2 row_mask:0xf bank_mask:0xf
	v_fmac_f32_dpp v250, v204, v146 row_ror:2 row_mask:0xf bank_mask:0xf
	v_fmac_f32_dpp v251, v205, v147 row_ror:2 row_mask:0xf bank_mask:0xf
	v_pk_mul_f32 v[224:225], v[220:221], s[100:101] op_sel_hi:[1,0]
	v_pk_mul_f32 v[190:191], v[222:223], s[100:101] op_sel_hi:[1,0]
	v_exp_f32_e32 v224, v224
	v_exp_f32_e32 v225, v225
	v_exp_f32_e32 v190, v190
	v_exp_f32_e32 v191, v191
	v_pk_mul_f32 v[220:221], v[220:221], v[248:249]
	v_pk_mul_f32 v[222:223], v[222:223], v[250:251]
	v_pk_add_f32 v[224:225], v[224:225], 1.0 op_sel_hi:[1,0]
	v_pk_add_f32 v[190:191], v[190:191], 1.0 op_sel_hi:[1,0]
	v_rcp_f32_e32 v224, v224
	v_rcp_f32_e32 v225, v225
	v_rcp_f32_e32 v190, v190
	v_rcp_f32_e32 v191, v191
	v_pk_mul_f32 v[220:221], v[220:221], v[224:225]
	v_pk_mul_f32 v[222:223], v[222:223], v[190:191]
	v_cvt_pk_bf16_f32 v182, v220, v221
	v_cvt_pk_bf16_f32 v183, v222, v223
	s_waitcnt vmcnt(0) lgkmcnt(0)
	v_pk_mul_f32 v[60:61], v[60:61], v[226:227] op_sel_hi:[1,0]
	v_pk_mul_f32 v[62:63], v[62:63], v[226:227] op_sel_hi:[1,0]
	v_pk_mul_f32 v[56:57], v[56:57], v[226:227] op_sel_hi:[1,0]
	v_pk_mul_f32 v[58:59], v[58:59], v[226:227] op_sel_hi:[1,0]
	v_pk_fma_f32 v[220:221], v[108:109], v[60:61], v[100:101]
	v_pk_fma_f32 v[222:223], v[110:111], v[62:63], v[102:103]
	v_pk_fma_f32 v[248:249], v[104:105], v[56:57], v[96:97]
	v_pk_fma_f32 v[250:251], v[106:107], v[58:59], v[98:99]
	v_cndmask_b32_e64 v72, v60, v92, s[98:99]
	v_cndmask_b32_e64 v73, v61, v93, s[98:99]
	v_cndmask_b32_e64 v74, v62, v94, s[98:99]
	v_cndmask_b32_e64 v75, v63, v95, s[98:99]
	v_cndmask_b32_e64 v76, v56, v88, s[98:99]
	v_cndmask_b32_e64 v77, v57, v89, s[98:99]
	v_cndmask_b32_e64 v78, v58, v90, s[98:99]
	v_cndmask_b32_e64 v79, v59, v91, s[98:99]
	v_fmac_f32_dpp v220, v72, v116 row_ror:1 row_mask:0xf bank_mask:0xf
	v_fmac_f32_dpp v221, v73, v117 row_ror:1 row_mask:0xf bank_mask:0xf
	v_fmac_f32_dpp v222, v74, v118 row_ror:1 row_mask:0xf bank_mask:0xf
	v_fmac_f32_dpp v223, v75, v119 row_ror:1 row_mask:0xf bank_mask:0xf
	v_fmac_f32_dpp v248, v76, v112 row_ror:1 row_mask:0xf bank_mask:0xf
	v_fmac_f32_dpp v249, v77, v113 row_ror:1 row_mask:0xf bank_mask:0xf
	v_fmac_f32_dpp v250, v78, v114 row_ror:1 row_mask:0xf bank_mask:0xf
	v_fmac_f32_dpp v251, v79, v115 row_ror:1 row_mask:0xf bank_mask:0xf
	v_cndmask_b32_e64 v72, v92, v60, s[40:41]
	v_cndmask_b32_e64 v73, v93, v61, s[40:41]
	v_cndmask_b32_e64 v74, v94, v62, s[40:41]
	v_cndmask_b32_e64 v75, v95, v63, s[40:41]
	v_cndmask_b32_e64 v76, v88, v56, s[40:41]
	v_cndmask_b32_e64 v77, v89, v57, s[40:41]
	v_cndmask_b32_e64 v78, v90, v58, s[40:41]
	v_cndmask_b32_e64 v79, v91, v59, s[40:41]
	v_fmac_f32_dpp v220, v72, v124 row_ror:2 row_mask:0xf bank_mask:0xf
	v_fmac_f32_dpp v221, v73, v125 row_ror:2 row_mask:0xf bank_mask:0xf
	v_fmac_f32_dpp v222, v74, v126 row_ror:2 row_mask:0xf bank_mask:0xf
	v_fmac_f32_dpp v223, v75, v127 row_ror:2 row_mask:0xf bank_mask:0xf
	v_fmac_f32_dpp v248, v76, v120 row_ror:2 row_mask:0xf bank_mask:0xf
	v_fmac_f32_dpp v249, v77, v121 row_ror:2 row_mask:0xf bank_mask:0xf
	v_fmac_f32_dpp v250, v78, v122 row_ror:2 row_mask:0xf bank_mask:0xf
	v_fmac_f32_dpp v251, v79, v123 row_ror:2 row_mask:0xf bank_mask:0xf
	s_and_saveexec_b64 s[0:1], s[12:13]
	global_store_dwordx4 v239, v[220:223], s[84:85] offset:16
	global_store_dwordx4 v241, v[248:251], s[84:85] offset:16
	s_or_b64 exec, exec, s[0:1]
	v_pk_mul_f32 v[224:225], v[220:221], s[100:101] op_sel_hi:[1,0]
	v_pk_mul_f32 v[190:191], v[222:223], s[100:101] op_sel_hi:[1,0]
	v_exp_f32_e32 v224, v224
	v_exp_f32_e32 v225, v225
	v_exp_f32_e32 v190, v190
	v_exp_f32_e32 v191, v191
	v_pk_mul_f32 v[220:221], v[220:221], v[248:249]
; __device__ __forceinline__ unsigned cvt_pk_bf16(float lo, float hi) { unsigned r; asm volatile("v_cvt_pk_bf16_f32 %0, %1, %2" : "=v"(r) : "v"(lo), "v"(hi)); return r; }
; __device__ __forceinline__ float dpp_ror1(float x) { return __int_as_float(__builtin_amdgcn_update_dpp(0, __float_as_int(x), 0x121, 0xf, 0xf, false)); }
; __device__ __forceinline__ float dpp_ror2(float x) { return __int_as_float(__builtin_amdgcn_update_dpp(0, __float_as_int(x), 0x122, 0xf, 0xf, false)); }
;     __device__ __forceinline__ void operator()(const f32x4 (&acc)[2][2][4][2], const Unit& u, int wr, int wc, int fr, int fq) const {
;     ...
;                 for (int m = 0; m < 4; ++m) {
;                     f32x4 cur[2], h[2];
; #pragma unroll
;                     for (int bj = 0; bj < 2; ++bj) { cur[bj] = acc[ai][bj][m][n] * rs[ai][m]; f32x4 x1, x2;
; #pragma unroll
;                         for (int e = 0; e < 4; ++e) { const float c1 = dpp_ror1(cur[bj][e]), p1 = dpp_ror1(pg[bj][e]), c2 = dpp_ror2(cur[bj][e]), p2 = dpp_ror2(pg[bj][e]);
;                             x1[e] = fr >= 1 ? c1 : p1; x2[e] = fr >= 2 ? c2 : p2; }
;                         h[bj] = bb[bj] + w0[bj] * x2 + w1[bj] * x1 + w2[bj] * cur[bj]; }
;                     if (ai == 0 && wr == 0 && m == 0 && fr < 2) {
;                         *(f32x4*)(hc0 + (size_t)(u.pm * 2 + fr) * FF2 + gcol + 4 * n) = h[0]; *(f32x4*)(hc0 + (size_t)(u.pm * 2 + fr) * FF2 + FF + gcol + 4 * n) = h[1]; }
;                     f32x4 a;
; #pragma unroll
;                     for (int e = 0; e < 4; ++e) { const float g = h[0][e]; a[e] = g * __builtin_amdgcn_rcpf(1.0f + __builtin_amdgcn_exp2f(-1.4426950408889634f * g)) * h[1][e]; }
;                     const unsigned p0 = cvt_pk_bf16(a[0], a[1]), p1 = cvt_pk_bf16(a[2], a[3]);
;                     if (n == 0) { pk_lo[ai][m][0] = p0; pk_lo[ai][m][1] = p1; }
;                     else { u32x4 w; w.x = pk_lo[ai][m][0]; w.y = pk_lo[ai][m][1]; w.z = p0; w.w = p1;
;                         *(u32x4*)(act + (size_t)(u.pm * BM + ai * HALF + wr * 64 + m * 16 + fr) * FF + gcol) = w; }
	v_pk_mul_f32 v[222:223], v[222:223], v[250:251]
	v_pk_add_f32 v[224:225], v[224:225], 1.0 op_sel_hi:[1,0]
	v_pk_add_f32 v[190:191], v[190:191], 1.0 op_sel_hi:[1,0]
	v_rcp_f32_e32 v224, v224
	v_rcp_f32_e32 v225, v225
	v_rcp_f32_e32 v190, v190
	v_rcp_f32_e32 v191, v191
	v_pk_mul_f32 v[220:221], v[220:221], v[224:225]
	v_pk_mul_f32 v[222:223], v[222:223], v[190:191]
	v_cvt_pk_bf16_f32 v188, v220, v221
	v_cvt_pk_bf16_f32 v189, v222, v223
	global_store_dwordx4 v237, v[186:189], s[24:25]
	v_pk_mul_f32 v[52:53], v[52:53], v[228:229] op_sel_hi:[1,0]
	v_pk_mul_f32 v[54:55], v[54:55], v[228:229] op_sel_hi:[1,0]
	v_pk_mul_f32 v[48:49], v[48:49], v[228:229] op_sel_hi:[1,0]
	v_pk_mul_f32 v[50:51], v[50:51], v[228:229] op_sel_hi:[1,0]
	v_pk_fma_f32 v[220:221], v[108:109], v[52:53], v[100:101]
	v_pk_fma_f32 v[222:223], v[110:111], v[54:55], v[102:103]
	v_pk_fma_f32 v[248:249], v[104:105], v[48:49], v[96:97]
	v_pk_fma_f32 v[250:251], v[106:107], v[50:51], v[98:99]
	v_cndmask_b32_e64 v72, v52, v60, s[98:99]
	v_cndmask_b32_e64 v73, v53, v61, s[98:99]
	v_cndmask_b32_e64 v74, v54, v62, s[98:99]
	v_cndmask_b32_e64 v75, v55, v63, s[98:99]
	v_cndmask_b32_e64 v76, v48, v56, s[98:99]
	v_cndmask_b32_e64 v77, v49, v57, s[98:99]
	v_cndmask_b32_e64 v78, v50, v58, s[98:99]
	v_cndmask_b32_e64 v79, v51, v59, s[98:99]
	v_fmac_f32_dpp v220, v72, v116 row_ror:1 row_mask:0xf bank_mask:0xf
	v_fmac_f32_dpp v221, v73, v117 row_ror:1 row_mask:0xf bank_mask:0xf
	v_fmac_f32_dpp v222, v74, v118 row_ror:1 row_mask:0xf bank_mask:0xf
	v_fmac_f32_dpp v223, v75, v119 row_ror:1 row_mask:0xf bank_mask:0xf
	v_fmac_f32_dpp v248, v76, v112 row_ror:1 row_mask:0xf bank_mask:0xf
	v_fmac_f32_dpp v249, v77, v113 row_ror:1 row_mask:0xf bank_mask:0xf
	v_fmac_f32_dpp v250, v78, v114 row_ror:1 row_mask:0xf bank_mask:0xf
	v_fmac_f32_dpp v251, v79, v115 row_ror:1 row_mask:0xf bank_mask:0xf
	v_cndmask_b32_e64 v72, v60, v52, s[40:41]
	v_cndmask_b32_e64 v73, v61, v53, s[40:41]
	v_cndmask_b32_e64 v74, v62, v54, s[40:41]
	v_cndmask_b32_e64 v75, v63, v55, s[40:41]
	v_cndmask_b32_e64 v76, v56, v48, s[40:41]
	v_cndmask_b32_e64 v77, v57, v49, s[40:41]
	v_cndmask_b32_e64 v78, v58, v50, s[40:41]
	v_cndmask_b32_e64 v79, v59, v51, s[40:41]
	v_fmac_f32_dpp v220, v72, v124 row_ror:2 row_mask:0xf bank_mask:0xf
	v_fmac_f32_dpp v221, v73, v125 row_ror:2 row_mask:0xf bank_mask:0xf
	v_fmac_f32_dpp v222, v74, v126 row_ror:2 row_mask:0xf bank_mask:0xf
	v_fmac_f32_dpp v223, v75, v127 row_ror:2 row_mask:0xf bank_mask:0xf
	v_fmac_f32_dpp v248, v76, v120 row_ror:2 row_mask:0xf bank_mask:0xf
	v_fmac_f32_dpp v249, v77, v121 row_ror:2 row_mask:0xf bank_mask:0xf
	v_fmac_f32_dpp v250, v78, v122 row_ror:2 row_mask:0xf bank_mask:0xf
	v_fmac_f32_dpp v251, v79, v123 row_ror:2 row_mask:0xf bank_mask:0xf
	v_pk_mul_f32 v[224:225], v[220:221], s[100:101] op_sel_hi:[1,0]
	v_pk_mul_f32 v[190:191], v[222:223], s[100:101] op_sel_hi:[1,0]
	v_exp_f32_e32 v224, v224
	v_exp_f32_e32 v225, v225
	v_exp_f32_e32 v190, v190
	v_exp_f32_e32 v191, v191
	v_pk_mul_f32 v[220:221], v[220:221], v[248:249]
	v_pk_mul_f32 v[222:223], v[222:223], v[250:251]
	v_pk_add_f32 v[224:225], v[224:225], 1.0 op_sel_hi:[1,0]
	v_pk_add_f32 v[190:191], v[190:191], 1.0 op_sel_hi:[1,0]
	v_rcp_f32_e32 v224, v224
	v_rcp_f32_e32 v225, v225
	v_rcp_f32_e32 v190, v190
	v_rcp_f32_e32 v191, v191
	v_pk_mul_f32 v[220:221], v[220:221], v[224:225]
	v_pk_mul_f32 v[222:223], v[222:223], v[190:191]
	v_cvt_pk_bf16_f32 v196, v220, v221
	v_cvt_pk_bf16_f32 v197, v222, v223
	v_add_u32_e32 v243, 0x16000, v237
	global_store_dwordx4 v243, v[194:197], s[24:25]
	v_pk_mul_f32 v[44:45], v[44:45], v[230:231] op_sel_hi:[1,0]
	v_pk_mul_f32 v[46:47], v[46:47], v[230:231] op_sel_hi:[1,0]
	v_pk_mul_f32 v[40:41], v[40:41], v[230:231] op_sel_hi:[1,0]
	v_pk_mul_f32 v[42:43], v[42:43], v[230:231] op_sel_hi:[1,0]
	v_pk_fma_f32 v[220:221], v[108:109], v[44:45], v[100:101]
	v_pk_fma_f32 v[222:223], v[110:111], v[46:47], v[102:103]
	v_pk_fma_f32 v[248:249], v[104:105], v[40:41], v[96:97]
	v_pk_fma_f32 v[250:251], v[106:107], v[42:43], v[98:99]
	v_cndmask_b32_e64 v72, v44, v52, s[98:99]
	v_cndmask_b32_e64 v73, v45, v53, s[98:99]
	v_cndmask_b32_e64 v74, v46, v54, s[98:99]
	v_cndmask_b32_e64 v75, v47, v55, s[98:99]
	v_cndmask_b32_e64 v76, v40, v48, s[98:99]
	v_cndmask_b32_e64 v77, v41, v49, s[98:99]
	v_cndmask_b32_e64 v78, v42, v50, s[98:99]
	v_cndmask_b32_e64 v79, v43, v51, s[98:99]
	v_fmac_f32_dpp v220, v72, v116 row_ror:1 row_mask:0xf bank_mask:0xf
	v_fmac_f32_dpp v221, v73, v117 row_ror:1 row_mask:0xf bank_mask:0xf
	v_fmac_f32_dpp v222, v74, v118 row_ror:1 row_mask:0xf bank_mask:0xf
	v_fmac_f32_dpp v223, v75, v119 row_ror:1 row_mask:0xf bank_mask:0xf
	v_fmac_f32_dpp v248, v76, v112 row_ror:1 row_mask:0xf bank_mask:0xf
	v_fmac_f32_dpp v249, v77, v113 row_ror:1 row_mask:0xf bank_mask:0xf
	v_fmac_f32_dpp v250, v78, v114 row_ror:1 row_mask:0xf bank_mask:0xf
	v_fmac_f32_dpp v251, v79, v115 row_ror:1 row_mask:0xf bank_mask:0xf
	v_cndmask_b32_e64 v72, v52, v44, s[40:41]
	v_cndmask_b32_e64 v73, v53, v45, s[40:41]
	v_cndmask_b32_e64 v74, v54, v46, s[40:41]
	v_cndmask_b32_e64 v75, v55, v47, s[40:41]
	v_cndmask_b32_e64 v76, v48, v40, s[40:41]
	v_cndmask_b32_e64 v77, v49, v41, s[40:41]
	v_cndmask_b32_e64 v78, v50, v42, s[40:41]
	v_cndmask_b32_e64 v79, v51, v43, s[40:41]
	v_fmac_f32_dpp v220, v72, v124 row_ror:2 row_mask:0xf bank_mask:0xf
	v_fmac_f32_dpp v221, v73, v125 row_ror:2 row_mask:0xf bank_mask:0xf
	v_fmac_f32_dpp v222, v74, v126 row_ror:2 row_mask:0xf bank_mask:0xf
	v_fmac_f32_dpp v223, v75, v127 row_ror:2 row_mask:0xf bank_mask:0xf
	v_fmac_f32_dpp v248, v76, v120 row_ror:2 row_mask:0xf bank_mask:0xf
; __device__ __forceinline__ unsigned cvt_pk_bf16(float lo, float hi) { unsigned r; asm volatile("v_cvt_pk_bf16_f32 %0, %1, %2" : "=v"(r) : "v"(lo), "v"(hi)); return r; }
; __device__ __forceinline__ float dpp_ror1(float x) { return __int_as_float(__builtin_amdgcn_update_dpp(0, __float_as_int(x), 0x121, 0xf, 0xf, false)); }
; __device__ __forceinline__ float dpp_ror2(float x) { return __int_as_float(__builtin_amdgcn_update_dpp(0, __float_as_int(x), 0x122, 0xf, 0xf, false)); }
;     __device__ __forceinline__ void operator()(const f32x4 (&acc)[2][2][4][2], const Unit& u, int wr, int wc, int fr, int fq) const {
;     ...
;                 for (int m = 0; m < 4; ++m) {
;                     f32x4 cur[2], h[2];
; #pragma unroll
;                     for (int bj = 0; bj < 2; ++bj) { cur[bj] = acc[ai][bj][m][n] * rs[ai][m]; f32x4 x1, x2;
; #pragma unroll
;                         for (int e = 0; e < 4; ++e) { const float c1 = dpp_ror1(cur[bj][e]), p1 = dpp_ror1(pg[bj][e]), c2 = dpp_ror2(cur[bj][e]), p2 = dpp_ror2(pg[bj][e]);
;                             x1[e] = fr >= 1 ? c1 : p1; x2[e] = fr >= 2 ? c2 : p2; }
;                         h[bj] = bb[bj] + w0[bj] * x2 + w1[bj] * x1 + w2[bj] * cur[bj]; }
;                     if (ai == 0 && wr == 0 && m == 0 && fr < 2) {
;                         *(f32x4*)(hc0 + (size_t)(u.pm * 2 + fr) * FF2 + gcol + 4 * n) = h[0]; *(f32x4*)(hc0 + (size_t)(u.pm * 2 + fr) * FF2 + FF + gcol + 4 * n) = h[1]; }
;                     f32x4 a;
; #pragma unroll
;                     for (int e = 0; e < 4; ++e) { const float g = h[0][e]; a[e] = g * __builtin_amdgcn_rcpf(1.0f + __builtin_amdgcn_exp2f(-1.4426950408889634f * g)) * h[1][e]; }
;                     const unsigned p0 = cvt_pk_bf16(a[0], a[1]), p1 = cvt_pk_bf16(a[2], a[3]);
;                     if (n == 0) { pk_lo[ai][m][0] = p0; pk_lo[ai][m][1] = p1; }
;                     else { u32x4 w; w.x = pk_lo[ai][m][0]; w.y = pk_lo[ai][m][1]; w.z = p0; w.w = p1;
;                         *(u32x4*)(act + (size_t)(u.pm * BM + ai * HALF + wr * 64 + m * 16 + fr) * FF + gcol) = w; }
	v_fmac_f32_dpp v249, v77, v121 row_ror:2 row_mask:0xf bank_mask:0xf
	v_fmac_f32_dpp v250, v78, v122 row_ror:2 row_mask:0xf bank_mask:0xf
	v_fmac_f32_dpp v251, v79, v123 row_ror:2 row_mask:0xf bank_mask:0xf
	v_pk_mul_f32 v[224:225], v[220:221], s[100:101] op_sel_hi:[1,0]
	v_pk_mul_f32 v[190:191], v[222:223], s[100:101] op_sel_hi:[1,0]
	v_exp_f32_e32 v224, v224
	v_exp_f32_e32 v225, v225
	v_exp_f32_e32 v190, v190
	v_exp_f32_e32 v191, v191
	v_pk_mul_f32 v[220:221], v[220:221], v[248:249]
	v_pk_mul_f32 v[222:223], v[222:223], v[250:251]
	v_pk_add_f32 v[224:225], v[224:225], 1.0 op_sel_hi:[1,0]
	v_pk_add_f32 v[190:191], v[190:191], 1.0 op_sel_hi:[1,0]
	v_rcp_f32_e32 v224, v224
	v_rcp_f32_e32 v225, v225
	v_rcp_f32_e32 v190, v190
	v_rcp_f32_e32 v191, v191
	v_pk_mul_f32 v[220:221], v[220:221], v[224:225]
	v_pk_mul_f32 v[222:223], v[222:223], v[190:191]
	v_cvt_pk_bf16_f32 v200, v220, v221
	v_cvt_pk_bf16_f32 v201, v222, v223
	v_add_u32_e32 v243, 0x2c000, v237
	global_store_dwordx4 v243, v[198:201], s[24:25]
	v_pk_fma_f32 v[220:221], v[108:109], v[36:37], v[100:101]
	v_pk_fma_f32 v[222:223], v[110:111], v[38:39], v[102:103]
	v_pk_fma_f32 v[248:249], v[104:105], v[32:33], v[96:97]
	v_pk_fma_f32 v[250:251], v[106:107], v[34:35], v[98:99]
	v_cndmask_b32_e64 v72, v36, v44, s[98:99]
	v_cndmask_b32_e64 v73, v37, v45, s[98:99]
	v_cndmask_b32_e64 v74, v38, v46, s[98:99]
	v_cndmask_b32_e64 v75, v39, v47, s[98:99]
	v_cndmask_b32_e64 v76, v32, v40, s[98:99]
	v_cndmask_b32_e64 v77, v33, v41, s[98:99]
	v_cndmask_b32_e64 v78, v34, v42, s[98:99]
	v_cndmask_b32_e64 v79, v35, v43, s[98:99]
	v_fmac_f32_dpp v220, v72, v116 row_ror:1 row_mask:0xf bank_mask:0xf
	v_fmac_f32_dpp v221, v73, v117 row_ror:1 row_mask:0xf bank_mask:0xf
	v_fmac_f32_dpp v222, v74, v118 row_ror:1 row_mask:0xf bank_mask:0xf
	v_fmac_f32_dpp v223, v75, v119 row_ror:1 row_mask:0xf bank_mask:0xf
	v_fmac_f32_dpp v248, v76, v112 row_ror:1 row_mask:0xf bank_mask:0xf
	v_fmac_f32_dpp v249, v77, v113 row_ror:1 row_mask:0xf bank_mask:0xf
	v_fmac_f32_dpp v250, v78, v114 row_ror:1 row_mask:0xf bank_mask:0xf
	v_fmac_f32_dpp v251, v79, v115 row_ror:1 row_mask:0xf bank_mask:0xf
	v_cndmask_b32_e64 v72, v44, v36, s[40:41]
	v_cndmask_b32_e64 v73, v45, v37, s[40:41]
	v_cndmask_b32_e64 v74, v46, v38, s[40:41]
	v_cndmask_b32_e64 v75, v47, v39, s[40:41]
	v_cndmask_b32_e64 v76, v40, v32, s[40:41]
	v_cndmask_b32_e64 v77, v41, v33, s[40:41]
	v_cndmask_b32_e64 v78, v42, v34, s[40:41]
	v_cndmask_b32_e64 v79, v43, v35, s[40:41]
	v_fmac_f32_dpp v220, v72, v124 row_ror:2 row_mask:0xf bank_mask:0xf
	v_fmac_f32_dpp v221, v73, v125 row_ror:2 row_mask:0xf bank_mask:0xf
	v_fmac_f32_dpp v222, v74, v126 row_ror:2 row_mask:0xf bank_mask:0xf
	v_fmac_f32_dpp v223, v75, v127 row_ror:2 row_mask:0xf bank_mask:0xf
	v_fmac_f32_dpp v248, v76, v120 row_ror:2 row_mask:0xf bank_mask:0xf
	v_fmac_f32_dpp v249, v77, v121 row_ror:2 row_mask:0xf bank_mask:0xf
	v_fmac_f32_dpp v250, v78, v122 row_ror:2 row_mask:0xf bank_mask:0xf
	v_fmac_f32_dpp v251, v79, v123 row_ror:2 row_mask:0xf bank_mask:0xf
	v_pk_mul_f32 v[224:225], v[220:221], s[100:101] op_sel_hi:[1,0]
	v_pk_mul_f32 v[190:191], v[222:223], s[100:101] op_sel_hi:[1,0]
	v_exp_f32_e32 v224, v224
	v_exp_f32_e32 v225, v225
	v_exp_f32_e32 v190, v190
	v_exp_f32_e32 v191, v191
	v_pk_mul_f32 v[220:221], v[220:221], v[248:249]
	v_pk_mul_f32 v[222:223], v[222:223], v[250:251]
	v_pk_add_f32 v[224:225], v[224:225], 1.0 op_sel_hi:[1,0]
	v_pk_add_f32 v[190:191], v[190:191], 1.0 op_sel_hi:[1,0]
	v_rcp_f32_e32 v224, v224
	v_rcp_f32_e32 v225, v225
	v_rcp_f32_e32 v190, v190
	v_rcp_f32_e32 v191, v191
	v_pk_mul_f32 v[220:221], v[220:221], v[224:225]
	v_pk_mul_f32 v[222:223], v[222:223], v[190:191]
	v_cvt_pk_bf16_f32 v204, v220, v221
	v_cvt_pk_bf16_f32 v205, v222, v223
	v_add_u32_e32 v243, 0x42000, v237
	global_store_dwordx4 v243, v[202:205], s[24:25]
	v_pk_mul_f32 v[28:29], v[28:29], v[234:235] op_sel_hi:[1,0]
	v_pk_mul_f32 v[30:31], v[30:31], v[234:235] op_sel_hi:[1,0]
	v_pk_mul_f32 v[24:25], v[24:25], v[234:235] op_sel_hi:[1,0]
	v_pk_mul_f32 v[26:27], v[26:27], v[234:235] op_sel_hi:[1,0]
	v_pk_fma_f32 v[220:221], v[108:109], v[28:29], v[100:101]
	v_pk_fma_f32 v[222:223], v[110:111], v[30:31], v[102:103]
	v_pk_fma_f32 v[248:249], v[104:105], v[24:25], v[96:97]
	v_pk_fma_f32 v[250:251], v[106:107], v[26:27], v[98:99]
	v_cndmask_b32_e64 v72, v28, v84, s[98:99]
	v_cndmask_b32_e64 v73, v29, v85, s[98:99]
	v_cndmask_b32_e64 v74, v30, v86, s[98:99]
	v_cndmask_b32_e64 v75, v31, v87, s[98:99]
	v_cndmask_b32_e64 v76, v24, v80, s[98:99]
	v_cndmask_b32_e64 v77, v25, v81, s[98:99]
	v_cndmask_b32_e64 v78, v26, v82, s[98:99]
	v_cndmask_b32_e64 v79, v27, v83, s[98:99]
	v_fmac_f32_dpp v220, v72, v116 row_ror:1 row_mask:0xf bank_mask:0xf
	v_fmac_f32_dpp v221, v73, v117 row_ror:1 row_mask:0xf bank_mask:0xf
	v_fmac_f32_dpp v222, v74, v118 row_ror:1 row_mask:0xf bank_mask:0xf
	v_fmac_f32_dpp v223, v75, v119 row_ror:1 row_mask:0xf bank_mask:0xf
	v_fmac_f32_dpp v248, v76, v112 row_ror:1 row_mask:0xf bank_mask:0xf
	v_fmac_f32_dpp v249, v77, v113 row_ror:1 row_mask:0xf bank_mask:0xf
	v_fmac_f32_dpp v250, v78, v114 row_ror:1 row_mask:0xf bank_mask:0xf
	v_fmac_f32_dpp v251, v79, v115 row_ror:1 row_mask:0xf bank_mask:0xf
	v_cndmask_b32_e64 v72, v84, v28, s[40:41]
	v_cndmask_b32_e64 v73, v85, v29, s[40:41]
	v_cndmask_b32_e64 v74, v86, v30, s[40:41]
	v_cndmask_b32_e64 v75, v87, v31, s[40:41]
	v_cndmask_b32_e64 v76, v80, v24, s[40:41]
	v_cndmask_b32_e64 v77, v81, v25, s[40:41]
	v_cndmask_b32_e64 v78, v82, v26, s[40:41]
	v_cndmask_b32_e64 v79, v83, v27, s[40:41]
	v_fmac_f32_dpp v220, v72, v124 row_ror:2 row_mask:0xf bank_mask:0xf
; __device__ __forceinline__ unsigned cvt_pk_bf16(float lo, float hi) { unsigned r; asm volatile("v_cvt_pk_bf16_f32 %0, %1, %2" : "=v"(r) : "v"(lo), "v"(hi)); return r; }
; __device__ __forceinline__ float dpp_ror1(float x) { return __int_as_float(__builtin_amdgcn_update_dpp(0, __float_as_int(x), 0x121, 0xf, 0xf, false)); }
; __device__ __forceinline__ float dpp_ror2(float x) { return __int_as_float(__builtin_amdgcn_update_dpp(0, __float_as_int(x), 0x122, 0xf, 0xf, false)); }
;     __device__ __forceinline__ void operator()(const f32x4 (&acc)[2][2][4][2], const Unit& u, int wr, int wc, int fr, int fq) const {
;     ...
;                 for (int m = 0; m < 4; ++m) {
;                     f32x4 cur[2], h[2];
; #pragma unroll
;                     for (int bj = 0; bj < 2; ++bj) { cur[bj] = acc[ai][bj][m][n] * rs[ai][m]; f32x4 x1, x2;
; #pragma unroll
;                         for (int e = 0; e < 4; ++e) { const float c1 = dpp_ror1(cur[bj][e]), p1 = dpp_ror1(pg[bj][e]), c2 = dpp_ror2(cur[bj][e]), p2 = dpp_ror2(pg[bj][e]);
;                             x1[e] = fr >= 1 ? c1 : p1; x2[e] = fr >= 2 ? c2 : p2; }
;                         h[bj] = bb[bj] + w0[bj] * x2 + w1[bj] * x1 + w2[bj] * cur[bj]; }
;                     if (ai == 0 && wr == 0 && m == 0 && fr < 2) {
;                         *(f32x4*)(hc0 + (size_t)(u.pm * 2 + fr) * FF2 + gcol + 4 * n) = h[0]; *(f32x4*)(hc0 + (size_t)(u.pm * 2 + fr) * FF2 + FF + gcol + 4 * n) = h[1]; }
;                     f32x4 a;
; #pragma unroll
;                     for (int e = 0; e < 4; ++e) { const float g = h[0][e]; a[e] = g * __builtin_amdgcn_rcpf(1.0f + __builtin_amdgcn_exp2f(-1.4426950408889634f * g)) * h[1][e]; }
;                     const unsigned p0 = cvt_pk_bf16(a[0], a[1]), p1 = cvt_pk_bf16(a[2], a[3]);
;                     if (n == 0) { pk_lo[ai][m][0] = p0; pk_lo[ai][m][1] = p1; }
;                     else { u32x4 w; w.x = pk_lo[ai][m][0]; w.y = pk_lo[ai][m][1]; w.z = p0; w.w = p1;
;                         *(u32x4*)(act + (size_t)(u.pm * BM + ai * HALF + wr * 64 + m * 16 + fr) * FF + gcol) = w; }
	v_fmac_f32_dpp v221, v73, v125 row_ror:2 row_mask:0xf bank_mask:0xf
	v_fmac_f32_dpp v222, v74, v126 row_ror:2 row_mask:0xf bank_mask:0xf
	v_fmac_f32_dpp v223, v75, v127 row_ror:2 row_mask:0xf bank_mask:0xf
	v_fmac_f32_dpp v248, v76, v120 row_ror:2 row_mask:0xf bank_mask:0xf
	v_fmac_f32_dpp v249, v77, v121 row_ror:2 row_mask:0xf bank_mask:0xf
	v_fmac_f32_dpp v250, v78, v122 row_ror:2 row_mask:0xf bank_mask:0xf
	v_fmac_f32_dpp v251, v79, v123 row_ror:2 row_mask:0xf bank_mask:0xf
	v_pk_mul_f32 v[224:225], v[220:221], s[100:101] op_sel_hi:[1,0]
	v_pk_mul_f32 v[190:191], v[222:223], s[100:101] op_sel_hi:[1,0]
	v_exp_f32_e32 v224, v224
	v_exp_f32_e32 v225, v225
	v_exp_f32_e32 v190, v190
	v_exp_f32_e32 v191, v191
	v_pk_mul_f32 v[220:221], v[220:221], v[248:249]
	v_pk_mul_f32 v[222:223], v[222:223], v[250:251]
	v_pk_add_f32 v[224:225], v[224:225], 1.0 op_sel_hi:[1,0]
	v_pk_add_f32 v[190:191], v[190:191], 1.0 op_sel_hi:[1,0]
	v_rcp_f32_e32 v224, v224
	v_rcp_f32_e32 v225, v225
	v_rcp_f32_e32 v190, v190
	v_rcp_f32_e32 v191, v191
	v_pk_mul_f32 v[220:221], v[220:221], v[224:225]
	v_pk_mul_f32 v[222:223], v[222:223], v[190:191]
	v_cvt_pk_bf16_f32 v162, v220, v221
	v_cvt_pk_bf16_f32 v163, v222, v223
	v_add_u32_e32 v243, 0xb0000, v237
	global_store_dwordx4 v243, v[160:163], s[24:25]
	v_pk_mul_f32 v[20:21], v[20:21], v[236:237] op_sel_hi:[1,0]
	v_pk_mul_f32 v[22:23], v[22:23], v[236:237] op_sel_hi:[1,0]
	v_pk_mul_f32 v[16:17], v[16:17], v[236:237] op_sel_hi:[1,0]
	v_pk_mul_f32 v[18:19], v[18:19], v[236:237] op_sel_hi:[1,0]
	v_pk_fma_f32 v[220:221], v[108:109], v[20:21], v[100:101]
	v_pk_fma_f32 v[222:223], v[110:111], v[22:23], v[102:103]
	v_pk_fma_f32 v[248:249], v[104:105], v[16:17], v[96:97]
	v_pk_fma_f32 v[250:251], v[106:107], v[18:19], v[98:99]
	v_cndmask_b32_e64 v72, v20, v28, s[98:99]
	v_cndmask_b32_e64 v73, v21, v29, s[98:99]
	v_cndmask_b32_e64 v74, v22, v30, s[98:99]
	v_cndmask_b32_e64 v75, v23, v31, s[98:99]
	v_cndmask_b32_e64 v76, v16, v24, s[98:99]
	v_cndmask_b32_e64 v77, v17, v25, s[98:99]
	v_cndmask_b32_e64 v78, v18, v26, s[98:99]
	v_cndmask_b32_e64 v79, v19, v27, s[98:99]
	v_fmac_f32_dpp v220, v72, v116 row_ror:1 row_mask:0xf bank_mask:0xf
	v_fmac_f32_dpp v221, v73, v117 row_ror:1 row_mask:0xf bank_mask:0xf
	v_fmac_f32_dpp v222, v74, v118 row_ror:1 row_mask:0xf bank_mask:0xf
	v_fmac_f32_dpp v223, v75, v119 row_ror:1 row_mask:0xf bank_mask:0xf
	v_fmac_f32_dpp v248, v76, v112 row_ror:1 row_mask:0xf bank_mask:0xf
	v_fmac_f32_dpp v249, v77, v113 row_ror:1 row_mask:0xf bank_mask:0xf
	v_fmac_f32_dpp v250, v78, v114 row_ror:1 row_mask:0xf bank_mask:0xf
	v_fmac_f32_dpp v251, v79, v115 row_ror:1 row_mask:0xf bank_mask:0xf
	v_cndmask_b32_e64 v72, v28, v20, s[40:41]
	v_cndmask_b32_e64 v73, v29, v21, s[40:41]
	v_cndmask_b32_e64 v74, v30, v22, s[40:41]
	v_cndmask_b32_e64 v75, v31, v23, s[40:41]
	v_cndmask_b32_e64 v76, v24, v16, s[40:41]
	v_cndmask_b32_e64 v77, v25, v17, s[40:41]
	v_cndmask_b32_e64 v78, v26, v18, s[40:41]
	v_cndmask_b32_e64 v79, v27, v19, s[40:41]
	v_fmac_f32_dpp v220, v72, v124 row_ror:2 row_mask:0xf bank_mask:0xf
	v_fmac_f32_dpp v221, v73, v125 row_ror:2 row_mask:0xf bank_mask:0xf
	v_fmac_f32_dpp v222, v74, v126 row_ror:2 row_mask:0xf bank_mask:0xf
	v_fmac_f32_dpp v223, v75, v127 row_ror:2 row_mask:0xf bank_mask:0xf
	v_fmac_f32_dpp v248, v76, v120 row_ror:2 row_mask:0xf bank_mask:0xf
	v_fmac_f32_dpp v249, v77, v121 row_ror:2 row_mask:0xf bank_mask:0xf
	v_fmac_f32_dpp v250, v78, v122 row_ror:2 row_mask:0xf bank_mask:0xf
	v_fmac_f32_dpp v251, v79, v123 row_ror:2 row_mask:0xf bank_mask:0xf
	v_pk_mul_f32 v[224:225], v[220:221], s[100:101] op_sel_hi:[1,0]
	v_pk_mul_f32 v[190:191], v[222:223], s[100:101] op_sel_hi:[1,0]
	v_exp_f32_e32 v224, v224
	v_exp_f32_e32 v225, v225
	v_exp_f32_e32 v190, v190
	v_exp_f32_e32 v191, v191
	v_pk_mul_f32 v[220:221], v[220:221], v[248:249]
	v_pk_mul_f32 v[222:223], v[222:223], v[250:251]
	v_pk_add_f32 v[224:225], v[224:225], 1.0 op_sel_hi:[1,0]
	v_pk_add_f32 v[190:191], v[190:191], 1.0 op_sel_hi:[1,0]
	v_rcp_f32_e32 v224, v224
	v_rcp_f32_e32 v225, v225
	v_rcp_f32_e32 v190, v190
	v_rcp_f32_e32 v191, v191
	v_pk_mul_f32 v[220:221], v[220:221], v[224:225]
	v_pk_mul_f32 v[222:223], v[222:223], v[190:191]
	v_cvt_pk_bf16_f32 v166, v220, v221
	v_cvt_pk_bf16_f32 v167, v222, v223
	v_add_u32_e32 v243, 0xc6000, v237
	global_store_dwordx4 v243, v[164:167], s[24:25]
	v_pk_mul_f32 v[12:13], v[12:13], v[238:239] op_sel_hi:[1,0]
	v_pk_mul_f32 v[14:15], v[14:15], v[238:239] op_sel_hi:[1,0]
	v_pk_mul_f32 v[8:9], v[8:9], v[238:239] op_sel_hi:[1,0]
	v_pk_mul_f32 v[10:11], v[10:11], v[238:239] op_sel_hi:[1,0]
	v_pk_fma_f32 v[220:221], v[108:109], v[12:13], v[100:101]
	v_pk_fma_f32 v[222:223], v[110:111], v[14:15], v[102:103]
	v_pk_fma_f32 v[248:249], v[104:105], v[8:9], v[96:97]
	v_pk_fma_f32 v[250:251], v[106:107], v[10:11], v[98:99]
	v_cndmask_b32_e64 v72, v12, v20, s[98:99]
	v_cndmask_b32_e64 v73, v13, v21, s[98:99]
	v_cndmask_b32_e64 v74, v14, v22, s[98:99]
	v_cndmask_b32_e64 v75, v15, v23, s[98:99]
	v_cndmask_b32_e64 v76, v8, v16, s[98:99]
	v_cndmask_b32_e64 v77, v9, v17, s[98:99]
	v_cndmask_b32_e64 v78, v10, v18, s[98:99]
	v_cndmask_b32_e64 v79, v11, v19, s[98:99]
	v_fmac_f32_dpp v220, v72, v116 row_ror:1 row_mask:0xf bank_mask:0xf
	v_fmac_f32_dpp v221, v73, v117 row_ror:1 row_mask:0xf bank_mask:0xf
; #define PG8_LAS __attribute__((address_space(3)))
; __device__ __forceinline__ unsigned cvt_pk_bf16(float lo, float hi) { unsigned r; asm volatile("v_cvt_pk_bf16_f32 %0, %1, %2" : "=v"(r) : "v"(lo), "v"(hi)); return r; }
; __device__ __forceinline__ float dpp_ror1(float x) { return __int_as_float(__builtin_amdgcn_update_dpp(0, __float_as_int(x), 0x121, 0xf, 0xf, false)); }
;     __device__ __forceinline__ void operator()(const f32x4 (&acc)[2][2][4][2], const Unit& u, int wr, int wc, int fr, int fq) const {
;     ...
;                     for (int n = 0; n < 2; ++n) { const f32x4 x = acc[ai][bj][3][n] * rs[ai][3];
;                         *(PG8_LAS f32x4*)(halo + ((ai * 2 + wr) * 2 + (fr - 14)) * 256 + bj * HALF + lcol + 4 * n) = x;
;                         if (ai == 1 && wr == 1) *(f32x4*)(rawh + (size_t)(u.pm * 2 + (fr - 14)) * FF2 + bj * FF + gcol + 4 * n) = x; }
;     ...
;                 for (int m = 0; m < 4; ++m) {
;                     f32x4 cur[2], h[2];
; #pragma unroll
;                     for (int bj = 0; bj < 2; ++bj) { cur[bj] = acc[ai][bj][m][n] * rs[ai][m]; f32x4 x1, x2;
; #pragma unroll
;                         for (int e = 0; e < 4; ++e) { const float c1 = dpp_ror1(cur[bj][e]), p1 = dpp_ror1(pg[bj][e]), c2 = dpp_ror2(cur[bj][e]), p2 = dpp_ror2(pg[bj][e]);
;                             x1[e] = fr >= 1 ? c1 : p1; x2[e] = fr >= 2 ? c2 : p2; }
;                         h[bj] = bb[bj] + w0[bj] * x2 + w1[bj] * x1 + w2[bj] * cur[bj]; }
;                     if (ai == 0 && wr == 0 && m == 0 && fr < 2) {
;                         *(f32x4*)(hc0 + (size_t)(u.pm * 2 + fr) * FF2 + gcol + 4 * n) = h[0]; *(f32x4*)(hc0 + (size_t)(u.pm * 2 + fr) * FF2 + FF + gcol + 4 * n) = h[1]; }
;                     f32x4 a;
; #pragma unroll
;                     for (int e = 0; e < 4; ++e) { const float g = h[0][e]; a[e] = g * __builtin_amdgcn_rcpf(1.0f + __builtin_amdgcn_exp2f(-1.4426950408889634f * g)) * h[1][e]; }
;                     const unsigned p0 = cvt_pk_bf16(a[0], a[1]), p1 = cvt_pk_bf16(a[2], a[3]);
;                     if (n == 0) { pk_lo[ai][m][0] = p0; pk_lo[ai][m][1] = p1; }
;                     else { u32x4 w; w.x = pk_lo[ai][m][0]; w.y = pk_lo[ai][m][1]; w.z = p0; w.w = p1;
;                         *(u32x4*)(act + (size_t)(u.pm * BM + ai * HALF + wr * 64 + m * 16 + fr) * FF + gcol) = w; }
	v_fmac_f32_dpp v222, v74, v118 row_ror:1 row_mask:0xf bank_mask:0xf
	v_fmac_f32_dpp v223, v75, v119 row_ror:1 row_mask:0xf bank_mask:0xf
	v_fmac_f32_dpp v248, v76, v112 row_ror:1 row_mask:0xf bank_mask:0xf
	v_fmac_f32_dpp v249, v77, v113 row_ror:1 row_mask:0xf bank_mask:0xf
	v_fmac_f32_dpp v250, v78, v114 row_ror:1 row_mask:0xf bank_mask:0xf
	v_fmac_f32_dpp v251, v79, v115 row_ror:1 row_mask:0xf bank_mask:0xf
	v_cndmask_b32_e64 v72, v20, v12, s[40:41]
	v_cndmask_b32_e64 v73, v21, v13, s[40:41]
	v_cndmask_b32_e64 v74, v22, v14, s[40:41]
	v_cndmask_b32_e64 v75, v23, v15, s[40:41]
	v_cndmask_b32_e64 v76, v16, v8, s[40:41]
	v_cndmask_b32_e64 v77, v17, v9, s[40:41]
	v_cndmask_b32_e64 v78, v18, v10, s[40:41]
	v_cndmask_b32_e64 v79, v19, v11, s[40:41]
	v_fmac_f32_dpp v220, v72, v124 row_ror:2 row_mask:0xf bank_mask:0xf
	v_fmac_f32_dpp v221, v73, v125 row_ror:2 row_mask:0xf bank_mask:0xf
	v_fmac_f32_dpp v222, v74, v126 row_ror:2 row_mask:0xf bank_mask:0xf
	v_fmac_f32_dpp v223, v75, v127 row_ror:2 row_mask:0xf bank_mask:0xf
	v_fmac_f32_dpp v248, v76, v120 row_ror:2 row_mask:0xf bank_mask:0xf
	v_fmac_f32_dpp v249, v77, v121 row_ror:2 row_mask:0xf bank_mask:0xf
	v_fmac_f32_dpp v250, v78, v122 row_ror:2 row_mask:0xf bank_mask:0xf
	v_fmac_f32_dpp v251, v79, v123 row_ror:2 row_mask:0xf bank_mask:0xf
	v_pk_mul_f32 v[224:225], v[220:221], s[100:101] op_sel_hi:[1,0]
	v_pk_mul_f32 v[190:191], v[222:223], s[100:101] op_sel_hi:[1,0]
	v_exp_f32_e32 v224, v224
	v_exp_f32_e32 v225, v225
	v_exp_f32_e32 v190, v190
	v_exp_f32_e32 v191, v191
	v_pk_mul_f32 v[220:221], v[220:221], v[248:249]
	v_pk_mul_f32 v[222:223], v[222:223], v[250:251]
	v_pk_add_f32 v[224:225], v[224:225], 1.0 op_sel_hi:[1,0]
	v_pk_add_f32 v[190:191], v[190:191], 1.0 op_sel_hi:[1,0]
	v_rcp_f32_e32 v224, v224
	v_rcp_f32_e32 v225, v225
	v_rcp_f32_e32 v190, v190
	v_rcp_f32_e32 v191, v191
	v_pk_mul_f32 v[220:221], v[220:221], v[224:225]
	v_pk_mul_f32 v[222:223], v[222:223], v[190:191]
	v_cvt_pk_bf16_f32 v180, v220, v221
	v_cvt_pk_bf16_f32 v181, v222, v223
	v_add_u32_e32 v243, 0xdc000, v237
	global_store_dwordx4 v243, v[178:181], s[24:25]
	v_pk_fma_f32 v[220:221], v[108:109], v[4:5], v[100:101]
	v_pk_fma_f32 v[222:223], v[110:111], v[6:7], v[102:103]
	v_pk_fma_f32 v[248:249], v[104:105], v[0:1], v[96:97]
	v_pk_fma_f32 v[250:251], v[106:107], v[2:3], v[98:99]
	v_cndmask_b32_e64 v72, v4, v12, s[98:99]
	v_cndmask_b32_e64 v73, v5, v13, s[98:99]
	v_cndmask_b32_e64 v74, v6, v14, s[98:99]
	v_cndmask_b32_e64 v75, v7, v15, s[98:99]
	v_cndmask_b32_e64 v76, v0, v8, s[98:99]
	v_cndmask_b32_e64 v77, v1, v9, s[98:99]
	v_cndmask_b32_e64 v78, v2, v10, s[98:99]
	v_cndmask_b32_e64 v79, v3, v11, s[98:99]
	v_fmac_f32_dpp v220, v72, v116 row_ror:1 row_mask:0xf bank_mask:0xf
	v_fmac_f32_dpp v221, v73, v117 row_ror:1 row_mask:0xf bank_mask:0xf
	v_fmac_f32_dpp v222, v74, v118 row_ror:1 row_mask:0xf bank_mask:0xf
	v_fmac_f32_dpp v223, v75, v119 row_ror:1 row_mask:0xf bank_mask:0xf
	v_fmac_f32_dpp v248, v76, v112 row_ror:1 row_mask:0xf bank_mask:0xf
	v_fmac_f32_dpp v249, v77, v113 row_ror:1 row_mask:0xf bank_mask:0xf
	v_fmac_f32_dpp v250, v78, v114 row_ror:1 row_mask:0xf bank_mask:0xf
	v_fmac_f32_dpp v251, v79, v115 row_ror:1 row_mask:0xf bank_mask:0xf
	v_cndmask_b32_e64 v72, v12, v4, s[40:41]
	v_cndmask_b32_e64 v73, v13, v5, s[40:41]
	v_cndmask_b32_e64 v74, v14, v6, s[40:41]
	v_cndmask_b32_e64 v75, v15, v7, s[40:41]
	v_cndmask_b32_e64 v76, v8, v0, s[40:41]
	v_cndmask_b32_e64 v77, v9, v1, s[40:41]
	v_cndmask_b32_e64 v78, v10, v2, s[40:41]
	v_cndmask_b32_e64 v79, v11, v3, s[40:41]
	v_fmac_f32_dpp v220, v72, v124 row_ror:2 row_mask:0xf bank_mask:0xf
	v_fmac_f32_dpp v221, v73, v125 row_ror:2 row_mask:0xf bank_mask:0xf
	v_fmac_f32_dpp v222, v74, v126 row_ror:2 row_mask:0xf bank_mask:0xf
	v_fmac_f32_dpp v223, v75, v127 row_ror:2 row_mask:0xf bank_mask:0xf
	v_fmac_f32_dpp v248, v76, v120 row_ror:2 row_mask:0xf bank_mask:0xf
	v_fmac_f32_dpp v249, v77, v121 row_ror:2 row_mask:0xf bank_mask:0xf
	v_fmac_f32_dpp v250, v78, v122 row_ror:2 row_mask:0xf bank_mask:0xf
	v_fmac_f32_dpp v251, v79, v123 row_ror:2 row_mask:0xf bank_mask:0xf
	v_pk_mul_f32 v[224:225], v[220:221], s[100:101] op_sel_hi:[1,0]
	v_pk_mul_f32 v[190:191], v[222:223], s[100:101] op_sel_hi:[1,0]
	v_exp_f32_e32 v224, v224
	v_exp_f32_e32 v225, v225
	v_exp_f32_e32 v190, v190
	v_exp_f32_e32 v191, v191
	v_pk_mul_f32 v[220:221], v[220:221], v[248:249]
	v_pk_mul_f32 v[222:223], v[222:223], v[250:251]
	v_pk_add_f32 v[224:225], v[224:225], 1.0 op_sel_hi:[1,0]
	v_pk_add_f32 v[190:191], v[190:191], 1.0 op_sel_hi:[1,0]
	v_rcp_f32_e32 v224, v224
	v_rcp_f32_e32 v225, v225
	v_rcp_f32_e32 v190, v190
	v_rcp_f32_e32 v191, v191
	v_pk_mul_f32 v[220:221], v[220:221], v[224:225]
	v_pk_mul_f32 v[222:223], v[222:223], v[190:191]
	v_cvt_pk_bf16_f32 v184, v220, v221
	v_cvt_pk_bf16_f32 v185, v222, v223
	v_add_u32_e32 v243, 0xf2000, v237
	global_store_dwordx4 v243, v[182:185], s[24:25]
	s_and_b64 vcc, exec, s[20:21]
	s_cbranch_vccnz .Lp7_norawh
	s_mov_b64 s[0:1], exec
	s_andn2_b64 exec, exec, s[40:41]
	v_add_u32_e32 v227, s11, v210
	v_mad_u32_u24 v227, v227, s70, v231
	v_add_u32_e32 v229, 0x2c00, v227
	global_store_dwordx4 v227, v[68:71], s[18:19]
	global_store_dwordx4 v227, v[4:7], s[18:19] offset:16
	global_store_dwordx4 v229, v[64:67], s[18:19]
	global_store_dwordx4 v229, v[0:3], s[18:19] offset:16
	s_mov_b64 exec, s[0:1]
